# static s_setprio 1 for the leading wave half (waves 0-3) in 5 GEMM K-loops, per-segment flips removed; plus deferred rs atomics and swiglu rs-load hoist
# speedup vs baseline: 1.0179x; 1.0055x over previous
.LBB0_202:
	s_setprio 0
	s_waitcnt vmcnt(0)
	s_waitcnt lgkmcnt(0)
	s_barrier
	s_mov_b64 s[0:1], exec
	v_readlane_b32 s8, v241, 3
	v_readlane_b32 s9, v241, 4
	s_and_b64 s[8:9], s[0:1], s[8:9]
	s_mov_b64 exec, s[8:9]
	s_cbranch_execz .LBB0_205
	s_mov_b64 s[8:9], exec
	v_mbcnt_lo_u32_b32 v1, s8, 0
	buffer_wbl2 sc1
	s_waitcnt vmcnt(0)
	s_waitcnt vmcnt(0)
	v_mbcnt_hi_u32_b32 v1, s9, v1
	v_cmp_eq_u32_e32 vcc, 0, v1
	s_and_b64 s[10:11], exec, vcc
	s_mov_b64 exec, s[10:11]
	s_cbranch_execz .LBB0_205
	s_bcnt1_i32_b64 s8, s[8:9]
	v_mov_b32_e32 v1, s8
	global_atomic_add v159, v1, s[50:51]

.LBB0_269:
	s_cmp_lg_u64 s[38:39], 0
	s_cbranch_scc0 .Lsp_LBB0269
	s_setprio 1
.Lsp_LBB0269:
	s_or_b32 s54, s35, 1
	s_lshl_b64 s[16:17], s[54:55], 7
	s_add_i32 s54, s35, 2
	s_lshl_b64 s[44:45], s[54:55], 7
	s_add_u32 s46, s66, s44
	s_addc_u32 s47, s67, s45
	s_and_b64 vcc, s[14:15], exec
	s_cselect_b32 vcc_hi, s29, s47
	s_cselect_b32 vcc_lo, s65, s46
	s_add_u32 s44, s70, s44
	s_addc_u32 s45, s71, s45
	s_and_b64 s[14:15], s[14:15], exec
	s_cselect_b32 s15, s51, s45
	s_cselect_b32 s14, s30, s44
	s_add_i32 s44, 0, 0x10000
	v_add_u32_e32 v143, s44, v140
	s_add_i32 s45, 0, 0x14000
	ds_read_b128 v[136:139], v143
	ds_read_b128 v[144:147], v143 offset:1024
	ds_read_b128 v[148:151], v143 offset:2048
	ds_read_b128 v[152:155], v143 offset:3072
	v_add_u32_e32 v143, s45, v140
	ds_read_b128 v[168:171], v143
	ds_read_b128 v[172:175], v143 offset:1024
	ds_read_b128 v[176:179], v143 offset:2048
	ds_read_b128 v[180:183], v143 offset:3072
	s_add_u32 s16, s31, s16
	s_addc_u32 s17, s34, s17
	v_lshl_add_u64 v[156:157], s[16:17], 0, v[130:131]
	s_add_i32 m0, s73, 0xc000
	ds_read_b128 v[184:187], v142
	ds_read_b128 v[188:191], v142 offset:1024
	ds_read_b128 v[192:195], v142 offset:2048
	ds_read_b128 v[196:199], v142 offset:3072
	ds_read_b128 v[200:203], v142 offset:4096
	ds_read_b128 v[204:207], v142 offset:5120
	ds_read_b128 v[216:219], v142 offset:6144
	ds_read_b128 v[220:223], v142 offset:7168
	global_load_lds_dwordx4 v[156:157], off
	v_lshl_add_u64 v[156:157], s[16:17], 0, v[132:133]
	s_add_i32 m0, s73, 0xe000
	s_nop 0
	global_load_lds_dwordx4 v[156:157], off
	s_waitcnt vmcnt(8)
	s_waitcnt lgkmcnt(0)
	s_barrier
	s_waitcnt lgkmcnt(0)
	v_mfma_f32_16x16x32_bf16 v[122:125], v[136:139], v[184:187], v[122:125]
	v_mfma_f32_16x16x32_bf16 v[114:117], v[148:151], v[184:187], v[114:117]
	v_mfma_f32_16x16x32_bf16 v[106:109], v[136:139], v[192:195], v[106:109]
	v_mfma_f32_16x16x32_bf16 v[102:105], v[148:151], v[192:195], v[102:105]
	v_mfma_f32_16x16x32_bf16 v[90:93], v[136:139], v[200:203], v[90:93]
	v_mfma_f32_16x16x32_bf16 v[86:89], v[148:151], v[200:203], v[86:89]
	v_mfma_f32_16x16x32_bf16 v[74:77], v[136:139], v[216:219], v[74:77]
	v_mfma_f32_16x16x32_bf16 v[70:73], v[148:151], v[216:219], v[70:73]
	v_mfma_f32_16x16x32_bf16 v[122:125], v[144:147], v[188:191], v[122:125]
	v_mfma_f32_16x16x32_bf16 v[114:117], v[152:155], v[188:191], v[114:117]
	v_mfma_f32_16x16x32_bf16 v[106:109], v[144:147], v[196:199], v[106:109]
	v_mfma_f32_16x16x32_bf16 v[102:105], v[152:155], v[196:199], v[102:105]
	v_mfma_f32_16x16x32_bf16 v[90:93], v[144:147], v[204:207], v[90:93]
	v_mfma_f32_16x16x32_bf16 v[86:89], v[152:155], v[204:207], v[86:89]
	v_mfma_f32_16x16x32_bf16 v[74:77], v[144:147], v[220:223], v[74:77]
	v_mfma_f32_16x16x32_bf16 v[70:73], v[152:155], v[220:223], v[70:73]
	v_mfma_f32_16x16x32_bf16 v[126:129], v[168:171], v[184:187], v[126:129]
	v_mfma_f32_16x16x32_bf16 v[118:121], v[176:179], v[184:187], v[118:121]
	v_mfma_f32_16x16x32_bf16 v[110:113], v[168:171], v[192:195], v[110:113]
	v_mfma_f32_16x16x32_bf16 v[98:101], v[176:179], v[192:195], v[98:101]
	v_mfma_f32_16x16x32_bf16 v[94:97], v[168:171], v[200:203], v[94:97]
	v_mfma_f32_16x16x32_bf16 v[82:85], v[176:179], v[200:203], v[82:85]
	v_mfma_f32_16x16x32_bf16 v[78:81], v[168:171], v[216:219], v[78:81]
	v_mfma_f32_16x16x32_bf16 v[66:69], v[176:179], v[216:219], v[66:69]
	v_mfma_f32_16x16x32_bf16 v[126:129], v[172:175], v[188:191], v[126:129]
	v_mfma_f32_16x16x32_bf16 v[118:121], v[180:183], v[188:191], v[118:121]
	v_mfma_f32_16x16x32_bf16 v[110:113], v[172:175], v[196:199], v[110:113]
	v_mfma_f32_16x16x32_bf16 v[98:101], v[180:183], v[196:199], v[98:101]
	v_mfma_f32_16x16x32_bf16 v[94:97], v[172:175], v[204:207], v[94:97]
	v_mfma_f32_16x16x32_bf16 v[82:85], v[180:183], v[204:207], v[82:85]
	v_mfma_f32_16x16x32_bf16 v[78:81], v[172:175], v[220:223], v[78:81]
	v_mfma_f32_16x16x32_bf16 v[66:69], v[180:183], v[220:223], v[66:69]
	s_barrier
	s_add_i32 s16, s44, s61
	v_lshl_add_u64 v[156:157], s[14:15], 0, v[158:159]
	s_mov_b32 m0, s16
	ds_read_b128 v[184:187], v142 offset:16384
	ds_read_b128 v[188:191], v142 offset:17408
	ds_read_b128 v[192:195], v142 offset:18432
	ds_read_b128 v[196:199], v142 offset:19456
	ds_read_b128 v[200:203], v142 offset:20480
	ds_read_b128 v[204:207], v142 offset:21504
	ds_read_b128 v[216:219], v142 offset:22528
	ds_read_b128 v[220:223], v142 offset:23552
	global_load_lds_dwordx4 v[156:157], off
	s_add_i32 m0, s16, 0x2000
	s_add_u32 s16, s14, 0x80000
	v_lshl_add_u64 v[224:225], s[14:15], 0, v[134:135]
	s_addc_u32 s17, s15, 0
	s_add_i32 s44, s45, s61
	global_load_lds_dwordx4 v[224:225], off
	v_lshl_add_u64 v[226:227], s[16:17], 0, v[158:159]
	s_mov_b32 m0, s44
	v_lshl_add_u64 v[228:229], vcc, 0, v[132:133]
	global_load_lds_dwordx4 v[226:227], off
	v_lshl_add_u64 v[226:227], s[16:17], 0, v[134:135]
	s_add_i32 m0, s44, 0x2000
	s_nop 0
	global_load_lds_dwordx4 v[226:227], off
	v_lshl_add_u64 v[226:227], vcc, 0, v[130:131]
	s_mov_b32 m0, s73
	s_nop 0
	global_load_lds_dwordx4 v[226:227], off
	s_mov_b32 m0, s75
	s_nop 0
	global_load_lds_dwordx4 v[228:229], off
	s_waitcnt vmcnt(8)
	s_waitcnt lgkmcnt(0)
	s_barrier
	s_waitcnt lgkmcnt(0)
	v_mfma_f32_16x16x32_bf16 v[58:61], v[136:139], v[184:187], v[58:61]
	v_mfma_f32_16x16x32_bf16 v[54:57], v[148:151], v[184:187], v[54:57]
	v_mfma_f32_16x16x32_bf16 v[42:45], v[136:139], v[192:195], v[42:45]
	v_mfma_f32_16x16x32_bf16 v[38:41], v[148:151], v[192:195], v[38:41]
	v_mfma_f32_16x16x32_bf16 v[26:29], v[136:139], v[200:203], v[26:29]
	v_mfma_f32_16x16x32_bf16 v[22:25], v[148:151], v[200:203], v[22:25]
	v_mfma_f32_16x16x32_bf16 v[10:13], v[136:139], v[216:219], v[10:13]
	v_mfma_f32_16x16x32_bf16 v[2:5], v[148:151], v[216:219], v[2:5]
	v_mfma_f32_16x16x32_bf16 v[58:61], v[144:147], v[188:191], v[58:61]
	v_mfma_f32_16x16x32_bf16 v[54:57], v[152:155], v[188:191], v[54:57]
	v_mfma_f32_16x16x32_bf16 v[42:45], v[144:147], v[196:199], v[42:45]
	v_mfma_f32_16x16x32_bf16 v[38:41], v[152:155], v[196:199], v[38:41]
	v_mfma_f32_16x16x32_bf16 v[26:29], v[144:147], v[204:207], v[26:29]
	v_mfma_f32_16x16x32_bf16 v[22:25], v[152:155], v[204:207], v[22:25]
	v_mfma_f32_16x16x32_bf16 v[10:13], v[144:147], v[220:223], v[10:13]
	v_mfma_f32_16x16x32_bf16 v[2:5], v[152:155], v[220:223], v[2:5]
	v_mfma_f32_16x16x32_bf16 v[62:65], v[168:171], v[184:187], v[62:65]
	v_mfma_f32_16x16x32_bf16 v[50:53], v[176:179], v[184:187], v[50:53]
	v_mfma_f32_16x16x32_bf16 v[46:49], v[168:171], v[192:195], v[46:49]
	v_mfma_f32_16x16x32_bf16 v[34:37], v[176:179], v[192:195], v[34:37]
	v_mfma_f32_16x16x32_bf16 v[30:33], v[168:171], v[200:203], v[30:33]
	v_mfma_f32_16x16x32_bf16 v[18:21], v[176:179], v[200:203], v[18:21]
	v_mfma_f32_16x16x32_bf16 v[14:17], v[168:171], v[216:219], v[14:17]
	v_mfma_f32_16x16x32_bf16 v[6:9], v[176:179], v[216:219], v[6:9]
	v_mfma_f32_16x16x32_bf16 v[62:65], v[172:175], v[188:191], v[62:65]
	v_mfma_f32_16x16x32_bf16 v[50:53], v[180:183], v[188:191], v[50:53]
	v_mfma_f32_16x16x32_bf16 v[46:49], v[172:175], v[196:199], v[46:49]
	v_mfma_f32_16x16x32_bf16 v[34:37], v[180:183], v[196:199], v[34:37]
	v_mfma_f32_16x16x32_bf16 v[30:33], v[172:175], v[204:207], v[30:33]
	v_mfma_f32_16x16x32_bf16 v[18:21], v[180:183], v[204:207], v[18:21]
	v_mfma_f32_16x16x32_bf16 v[14:17], v[172:175], v[220:223], v[14:17]
	v_mfma_f32_16x16x32_bf16 v[6:9], v[180:183], v[220:223], v[6:9]
	s_barrier
	s_add_i32 s44, 0, 0x18000
	v_add_u32_e32 v143, s44, v140
	s_add_i32 s45, 0, 0x1c000
	ds_read_b128 v[136:139], v143
	ds_read_b128 v[144:147], v143 offset:1024
	ds_read_b128 v[148:151], v143 offset:2048
	ds_read_b128 v[152:155], v143 offset:3072
	v_add_u32_e32 v143, s45, v140
	ds_read_b128 v[168:171], v143
	ds_read_b128 v[172:175], v143 offset:1024
	ds_read_b128 v[176:179], v143 offset:2048
	ds_read_b128 v[180:183], v143 offset:3072
	s_add_u32 s16, vcc_lo, 0x80000
	s_addc_u32 s17, vcc_hi, 0
	s_mov_b32 m0, s24
	v_lshl_add_u64 v[230:231], s[16:17], 0, v[130:131]
	ds_read_b128 v[184:187], v142 offset:32768
	ds_read_b128 v[188:191], v142 offset:33792
	ds_read_b128 v[192:195], v142 offset:34816
	ds_read_b128 v[196:199], v142 offset:35840
	ds_read_b128 v[200:203], v142 offset:36864
	ds_read_b128 v[204:207], v142 offset:37888
	ds_read_b128 v[216:219], v142 offset:38912
	ds_read_b128 v[220:223], v142 offset:39936
	global_load_lds_dwordx4 v[230:231], off
	v_lshl_add_u64 v[230:231], s[16:17], 0, v[132:133]
	s_mov_b32 m0, s25
	s_nop 0
	global_load_lds_dwordx4 v[230:231], off
	s_waitcnt vmcnt(8)
	s_waitcnt lgkmcnt(0)
	s_barrier
	s_waitcnt lgkmcnt(0)
	v_mfma_f32_16x16x32_bf16 v[122:125], v[136:139], v[184:187], v[122:125]
	v_mfma_f32_16x16x32_bf16 v[114:117], v[148:151], v[184:187], v[114:117]
	v_mfma_f32_16x16x32_bf16 v[106:109], v[136:139], v[192:195], v[106:109]
	v_mfma_f32_16x16x32_bf16 v[102:105], v[148:151], v[192:195], v[102:105]
	v_mfma_f32_16x16x32_bf16 v[90:93], v[136:139], v[200:203], v[90:93]
	v_mfma_f32_16x16x32_bf16 v[86:89], v[148:151], v[200:203], v[86:89]
	v_mfma_f32_16x16x32_bf16 v[74:77], v[136:139], v[216:219], v[74:77]
	v_mfma_f32_16x16x32_bf16 v[70:73], v[148:151], v[216:219], v[70:73]
	v_mfma_f32_16x16x32_bf16 v[122:125], v[144:147], v[188:191], v[122:125]
	v_mfma_f32_16x16x32_bf16 v[114:117], v[152:155], v[188:191], v[114:117]
	v_mfma_f32_16x16x32_bf16 v[106:109], v[144:147], v[196:199], v[106:109]
	v_mfma_f32_16x16x32_bf16 v[102:105], v[152:155], v[196:199], v[102:105]
	v_mfma_f32_16x16x32_bf16 v[90:93], v[144:147], v[204:207], v[90:93]
	v_mfma_f32_16x16x32_bf16 v[86:89], v[152:155], v[204:207], v[86:89]
	v_mfma_f32_16x16x32_bf16 v[74:77], v[144:147], v[220:223], v[74:77]
	v_mfma_f32_16x16x32_bf16 v[70:73], v[152:155], v[220:223], v[70:73]
	v_mfma_f32_16x16x32_bf16 v[126:129], v[168:171], v[184:187], v[126:129]
	v_mfma_f32_16x16x32_bf16 v[118:121], v[176:179], v[184:187], v[118:121]
	v_mfma_f32_16x16x32_bf16 v[110:113], v[168:171], v[192:195], v[110:113]
	v_mfma_f32_16x16x32_bf16 v[98:101], v[176:179], v[192:195], v[98:101]
	v_mfma_f32_16x16x32_bf16 v[94:97], v[168:171], v[200:203], v[94:97]
	v_mfma_f32_16x16x32_bf16 v[82:85], v[176:179], v[200:203], v[82:85]
	v_mfma_f32_16x16x32_bf16 v[78:81], v[168:171], v[216:219], v[78:81]
	v_mfma_f32_16x16x32_bf16 v[66:69], v[176:179], v[216:219], v[66:69]
	v_mfma_f32_16x16x32_bf16 v[126:129], v[172:175], v[188:191], v[126:129]
	v_mfma_f32_16x16x32_bf16 v[118:121], v[180:183], v[188:191], v[118:121]
	v_mfma_f32_16x16x32_bf16 v[110:113], v[172:175], v[196:199], v[110:113]
	v_mfma_f32_16x16x32_bf16 v[98:101], v[180:183], v[196:199], v[98:101]
	v_mfma_f32_16x16x32_bf16 v[94:97], v[172:175], v[204:207], v[94:97]
	v_mfma_f32_16x16x32_bf16 v[82:85], v[180:183], v[204:207], v[82:85]
	v_mfma_f32_16x16x32_bf16 v[78:81], v[172:175], v[220:223], v[78:81]
	v_mfma_f32_16x16x32_bf16 v[66:69], v[180:183], v[220:223], v[66:69]
	s_barrier
	s_add_i32 s16, s44, s61
	v_lshl_add_u64 v[156:157], v[156:157], 0, s[56:57]
	s_mov_b32 m0, s16
	ds_read_b128 v[184:187], v142 offset:49152
	ds_read_b128 v[188:191], v142 offset:50176
	ds_read_b128 v[192:195], v142 offset:51200
	ds_read_b128 v[196:199], v142 offset:52224
	ds_read_b128 v[200:203], v142 offset:53248
	ds_read_b128 v[204:207], v142 offset:54272
	ds_read_b128 v[216:219], v142 offset:55296
	ds_read_b128 v[220:223], v142 offset:56320
	global_load_lds_dwordx4 v[156:157], off
	s_add_i32 m0, s16, 0x2000
	s_add_u32 s14, s14, 0x80080
	v_lshl_add_u64 v[156:157], v[224:225], 0, s[56:57]
	s_addc_u32 s15, s15, 0
	s_add_i32 s16, s45, s61
	global_load_lds_dwordx4 v[156:157], off
	v_lshl_add_u64 v[156:157], s[14:15], 0, v[158:159]
	s_mov_b32 m0, s16
	s_nop 0
	global_load_lds_dwordx4 v[156:157], off
	v_lshl_add_u64 v[156:157], s[14:15], 0, v[134:135]
	s_add_i32 m0, s16, 0x2000
	s_nop 0
	global_load_lds_dwordx4 v[156:157], off
	v_lshl_add_u64 v[156:157], v[226:227], 0, s[56:57]
	s_mov_b32 m0, s26
	s_nop 0
	global_load_lds_dwordx4 v[156:157], off
	v_lshl_add_u64 v[156:157], v[228:229], 0, s[56:57]
	s_mov_b32 m0, s27
	s_nop 0
	global_load_lds_dwordx4 v[156:157], off
	s_waitcnt vmcnt(8)
	s_waitcnt lgkmcnt(0)
	s_barrier
	s_waitcnt lgkmcnt(0)
	v_mfma_f32_16x16x32_bf16 v[58:61], v[136:139], v[184:187], v[58:61]
	v_mfma_f32_16x16x32_bf16 v[54:57], v[148:151], v[184:187], v[54:57]
	v_mfma_f32_16x16x32_bf16 v[42:45], v[136:139], v[192:195], v[42:45]
	v_mfma_f32_16x16x32_bf16 v[38:41], v[148:151], v[192:195], v[38:41]
	v_mfma_f32_16x16x32_bf16 v[26:29], v[136:139], v[200:203], v[26:29]
	v_mfma_f32_16x16x32_bf16 v[22:25], v[148:151], v[200:203], v[22:25]
	v_mfma_f32_16x16x32_bf16 v[10:13], v[136:139], v[216:219], v[10:13]
	v_mfma_f32_16x16x32_bf16 v[2:5], v[148:151], v[216:219], v[2:5]
	v_mfma_f32_16x16x32_bf16 v[58:61], v[144:147], v[188:191], v[58:61]
	v_mfma_f32_16x16x32_bf16 v[54:57], v[152:155], v[188:191], v[54:57]
	v_mfma_f32_16x16x32_bf16 v[42:45], v[144:147], v[196:199], v[42:45]
	v_mfma_f32_16x16x32_bf16 v[38:41], v[152:155], v[196:199], v[38:41]
	v_mfma_f32_16x16x32_bf16 v[26:29], v[144:147], v[204:207], v[26:29]
	v_mfma_f32_16x16x32_bf16 v[22:25], v[152:155], v[204:207], v[22:25]
	v_mfma_f32_16x16x32_bf16 v[10:13], v[144:147], v[220:223], v[10:13]
	v_mfma_f32_16x16x32_bf16 v[2:5], v[152:155], v[220:223], v[2:5]
	v_mfma_f32_16x16x32_bf16 v[62:65], v[168:171], v[184:187], v[62:65]
	v_mfma_f32_16x16x32_bf16 v[50:53], v[176:179], v[184:187], v[50:53]
	v_mfma_f32_16x16x32_bf16 v[46:49], v[168:171], v[192:195], v[46:49]
	v_mfma_f32_16x16x32_bf16 v[34:37], v[176:179], v[192:195], v[34:37]
	v_mfma_f32_16x16x32_bf16 v[30:33], v[168:171], v[200:203], v[30:33]
	v_mfma_f32_16x16x32_bf16 v[18:21], v[176:179], v[200:203], v[18:21]
	v_mfma_f32_16x16x32_bf16 v[14:17], v[168:171], v[216:219], v[14:17]
	v_mfma_f32_16x16x32_bf16 v[6:9], v[176:179], v[216:219], v[6:9]
	v_mfma_f32_16x16x32_bf16 v[62:65], v[172:175], v[188:191], v[62:65]
	v_mfma_f32_16x16x32_bf16 v[50:53], v[180:183], v[188:191], v[50:53]
	v_mfma_f32_16x16x32_bf16 v[46:49], v[172:175], v[196:199], v[46:49]
	v_mfma_f32_16x16x32_bf16 v[34:37], v[180:183], v[196:199], v[34:37]
	v_mfma_f32_16x16x32_bf16 v[30:33], v[172:175], v[204:207], v[30:33]
	v_mfma_f32_16x16x32_bf16 v[18:21], v[180:183], v[204:207], v[18:21]
	v_mfma_f32_16x16x32_bf16 v[14:17], v[172:175], v[220:223], v[14:17]
	v_mfma_f32_16x16x32_bf16 v[6:9], v[180:183], v[220:223], v[6:9]
	s_barrier
	s_cmp_gt_u32 s35, 29
	s_mov_b32 s35, s54
	s_cbranch_scc1 .LBB0_279

.LBB0_285:
	v_readlane_b32 s0, v240, 63
	s_add_i32 s10, s0, 1
	s_cmp_lt_i32 s10, s93
	s_cselect_b64 s[0:1], -1, 0
	s_and_b64 s[8:9], s[40:41], s[0:1]
	s_andn2_b64 vcc, exec, s[8:9]
	s_cbranch_vccnz .LBB0_335
	s_setprio 0
	s_waitcnt vmcnt(0)
	s_waitcnt lgkmcnt(0)
	s_barrier
	s_mov_b64 s[8:9], exec
	v_readlane_b32 s12, v241, 3
	v_readlane_b32 s13, v241, 4
	s_and_b64 s[12:13], s[8:9], s[12:13]
	s_mov_b64 exec, s[12:13]
	s_cbranch_execz .LBB0_334
	v_mov_b32_e32 v1, s97
	s_waitcnt vmcnt(0) expcnt(0) lgkmcnt(0)
	ds_read_b32 v3, v1
	ds_read_b32 v2, v1 offset:4
	s_waitcnt lgkmcnt(1)
	v_cmp_ne_u32_e32 vcc, 0, v3
	s_cbranch_vccnz .LBB0_302
	v_readlane_b32 s14, v244, 0
	v_readlane_b32 s15, v244, 1
	s_load_dwordx2 s[12:13], s[14:15], 0x4
	s_mov_b32 s11, 1
	s_waitcnt lgkmcnt(0)
	s_mul_i32 s3, s12, s96
	s_mul_i32 s3, s3, s13
	s_branch .LBB0_290

.LBB0_353:
	s_cmp_lg_u64 s[12:13], 0
	s_cbranch_scc0 .Lsp_LBB0353
	s_setprio 1
.Lsp_LBB0353:
	s_add_u32 s36, s0, 0x100
	s_addc_u32 s37, s1, 0
	s_add_i32 s27, 0, 0x10000
	s_cmpk_eq_i32 s26, 0x52
	s_cselect_b32 s69, s65, s37
	s_cselect_b32 s68, s64, s36
	v_add_u32_e32 v144, s27, v146
	s_cselect_b32 s15, s67, s25
	s_cselect_b32 s14, s66, s24
	s_add_i32 s28, 0, 0x14000
	ds_read_b128 v[140:143], v144
	ds_read_b128 v[150:153], v144 offset:1024
	ds_read_b128 v[154:157], v144 offset:2048
	ds_read_b128 v[168:171], v144 offset:3072
	v_add_u32_e32 v144, s28, v146
	ds_read_b128 v[172:175], v144
	ds_read_b128 v[176:179], v144 offset:1024
	ds_read_b128 v[180:183], v144 offset:2048
	ds_read_b128 v[184:187], v144 offset:3072
	v_lshl_add_u64 v[144:145], s[0:1], 0, v[136:137]
	s_add_i32 m0, s59, 0xc000
	ds_read_b128 v[188:191], v148
	ds_read_b128 v[192:195], v148 offset:1024
	ds_read_b128 v[196:199], v148 offset:2048
	ds_read_b128 v[200:203], v148 offset:3072
	ds_read_b128 v[204:207], v148 offset:4096
	ds_read_b128 v[216:219], v148 offset:5120
	ds_read_b128 v[220:223], v148 offset:6144
	ds_read_b128 v[224:227], v148 offset:7168
	global_load_lds_dwordx4 v[144:145], off
	v_lshl_add_u64 v[144:145], s[0:1], 0, v[138:139]
	s_add_i32 m0, s59, 0xe000
	s_nop 0
	global_load_lds_dwordx4 v[144:145], off
	s_waitcnt vmcnt(8)
	s_waitcnt lgkmcnt(0)
	s_barrier
	s_waitcnt lgkmcnt(0)
	v_mfma_f32_16x16x32_bf16 v[126:129], v[140:143], v[188:191], v[126:129]
	v_mfma_f32_16x16x32_bf16 v[122:125], v[154:157], v[188:191], v[122:125]
	v_mfma_f32_16x16x32_bf16 v[110:113], v[140:143], v[196:199], v[110:113]
	v_mfma_f32_16x16x32_bf16 v[106:109], v[154:157], v[196:199], v[106:109]
	v_mfma_f32_16x16x32_bf16 v[94:97], v[140:143], v[204:207], v[94:97]
	v_mfma_f32_16x16x32_bf16 v[90:93], v[154:157], v[204:207], v[90:93]
	v_mfma_f32_16x16x32_bf16 v[78:81], v[140:143], v[220:223], v[78:81]
	v_mfma_f32_16x16x32_bf16 v[74:77], v[154:157], v[220:223], v[74:77]
	v_mfma_f32_16x16x32_bf16 v[126:129], v[150:153], v[192:195], v[126:129]
	v_mfma_f32_16x16x32_bf16 v[122:125], v[168:171], v[192:195], v[122:125]
	v_mfma_f32_16x16x32_bf16 v[110:113], v[150:153], v[200:203], v[110:113]
	v_mfma_f32_16x16x32_bf16 v[106:109], v[168:171], v[200:203], v[106:109]
	v_mfma_f32_16x16x32_bf16 v[94:97], v[150:153], v[216:219], v[94:97]
	v_mfma_f32_16x16x32_bf16 v[90:93], v[168:171], v[216:219], v[90:93]
	v_mfma_f32_16x16x32_bf16 v[78:81], v[150:153], v[224:227], v[78:81]
	v_mfma_f32_16x16x32_bf16 v[74:77], v[168:171], v[224:227], v[74:77]
	v_mfma_f32_16x16x32_bf16 v[118:121], v[172:175], v[188:191], v[118:121]
	v_mfma_f32_16x16x32_bf16 v[114:117], v[180:183], v[188:191], v[114:117]
	v_mfma_f32_16x16x32_bf16 v[102:105], v[172:175], v[196:199], v[102:105]
	v_mfma_f32_16x16x32_bf16 v[98:101], v[180:183], v[196:199], v[98:101]
	v_mfma_f32_16x16x32_bf16 v[86:89], v[172:175], v[204:207], v[86:89]
	v_mfma_f32_16x16x32_bf16 v[82:85], v[180:183], v[204:207], v[82:85]
	v_mfma_f32_16x16x32_bf16 v[70:73], v[172:175], v[220:223], v[70:73]
	v_mfma_f32_16x16x32_bf16 v[66:69], v[180:183], v[220:223], v[66:69]
	v_mfma_f32_16x16x32_bf16 v[118:121], v[176:179], v[192:195], v[118:121]
	v_mfma_f32_16x16x32_bf16 v[114:117], v[184:187], v[192:195], v[114:117]
	v_mfma_f32_16x16x32_bf16 v[102:105], v[176:179], v[200:203], v[102:105]
	v_mfma_f32_16x16x32_bf16 v[98:101], v[184:187], v[200:203], v[98:101]
	v_mfma_f32_16x16x32_bf16 v[86:89], v[176:179], v[216:219], v[86:89]
	v_mfma_f32_16x16x32_bf16 v[82:85], v[184:187], v[216:219], v[82:85]
	v_mfma_f32_16x16x32_bf16 v[70:73], v[176:179], v[224:227], v[70:73]
	v_mfma_f32_16x16x32_bf16 v[66:69], v[184:187], v[224:227], v[66:69]
	s_barrier
	s_add_i32 s0, s27, s58
	v_lshl_add_u64 v[144:145], s[14:15], 0, v[158:159]
	s_mov_b32 m0, s0
	ds_read_b128 v[188:191], v148 offset:16384
	ds_read_b128 v[192:195], v148 offset:17408
	ds_read_b128 v[196:199], v148 offset:18432
	ds_read_b128 v[200:203], v148 offset:19456
	ds_read_b128 v[204:207], v148 offset:20480
	ds_read_b128 v[216:219], v148 offset:21504
	ds_read_b128 v[220:223], v148 offset:22528
	ds_read_b128 v[224:227], v148 offset:23552
	global_load_lds_dwordx4 v[144:145], off
	s_add_i32 m0, s0, 0x2000
	s_add_u32 s0, s14, 0x158000
	v_lshl_add_u64 v[228:229], s[14:15], 0, v[134:135]
	s_addc_u32 s1, s15, 0
	s_add_i32 s27, s28, s58
	global_load_lds_dwordx4 v[228:229], off
	v_lshl_add_u64 v[230:231], s[0:1], 0, v[158:159]
	s_mov_b32 m0, s27
	v_lshl_add_u64 v[232:233], s[68:69], 0, v[132:133]
	global_load_lds_dwordx4 v[230:231], off
	v_lshl_add_u64 v[230:231], s[0:1], 0, v[134:135]
	s_add_i32 m0, s27, 0x2000
	s_nop 0
	global_load_lds_dwordx4 v[230:231], off
	v_lshl_add_u64 v[230:231], s[68:69], 0, v[130:131]
	s_mov_b32 m0, s59
	s_nop 0
	global_load_lds_dwordx4 v[230:231], off
	s_mov_b32 m0, s70
	s_nop 0
	global_load_lds_dwordx4 v[232:233], off
	s_waitcnt vmcnt(8)
	s_waitcnt lgkmcnt(0)
	s_barrier
	s_waitcnt lgkmcnt(0)
	v_mfma_f32_16x16x32_bf16 v[62:65], v[140:143], v[188:191], v[62:65]
	v_mfma_f32_16x16x32_bf16 v[58:61], v[154:157], v[188:191], v[58:61]
	v_mfma_f32_16x16x32_bf16 v[46:49], v[140:143], v[196:199], v[46:49]
	v_mfma_f32_16x16x32_bf16 v[42:45], v[154:157], v[196:199], v[42:45]
	v_mfma_f32_16x16x32_bf16 v[30:33], v[140:143], v[204:207], v[30:33]
	v_mfma_f32_16x16x32_bf16 v[26:29], v[154:157], v[204:207], v[26:29]
	v_mfma_f32_16x16x32_bf16 v[14:17], v[140:143], v[220:223], v[14:17]
	v_mfma_f32_16x16x32_bf16 v[10:13], v[154:157], v[220:223], v[10:13]
	v_mfma_f32_16x16x32_bf16 v[62:65], v[150:153], v[192:195], v[62:65]
	v_mfma_f32_16x16x32_bf16 v[58:61], v[168:171], v[192:195], v[58:61]
	v_mfma_f32_16x16x32_bf16 v[46:49], v[150:153], v[200:203], v[46:49]
	v_mfma_f32_16x16x32_bf16 v[42:45], v[168:171], v[200:203], v[42:45]
	v_mfma_f32_16x16x32_bf16 v[30:33], v[150:153], v[216:219], v[30:33]
	v_mfma_f32_16x16x32_bf16 v[26:29], v[168:171], v[216:219], v[26:29]
	v_mfma_f32_16x16x32_bf16 v[14:17], v[150:153], v[224:227], v[14:17]
	v_mfma_f32_16x16x32_bf16 v[10:13], v[168:171], v[224:227], v[10:13]
	v_mfma_f32_16x16x32_bf16 v[54:57], v[172:175], v[188:191], v[54:57]
	v_mfma_f32_16x16x32_bf16 v[50:53], v[180:183], v[188:191], v[50:53]
	v_mfma_f32_16x16x32_bf16 v[38:41], v[172:175], v[196:199], v[38:41]
	v_mfma_f32_16x16x32_bf16 v[34:37], v[180:183], v[196:199], v[34:37]
	v_mfma_f32_16x16x32_bf16 v[22:25], v[172:175], v[204:207], v[22:25]
	v_mfma_f32_16x16x32_bf16 v[18:21], v[180:183], v[204:207], v[18:21]
	v_mfma_f32_16x16x32_bf16 v[6:9], v[172:175], v[220:223], v[6:9]
	v_mfma_f32_16x16x32_bf16 v[2:5], v[180:183], v[220:223], v[2:5]
	v_mfma_f32_16x16x32_bf16 v[54:57], v[176:179], v[192:195], v[54:57]
	v_mfma_f32_16x16x32_bf16 v[50:53], v[184:187], v[192:195], v[50:53]
	v_mfma_f32_16x16x32_bf16 v[38:41], v[176:179], v[200:203], v[38:41]
	v_mfma_f32_16x16x32_bf16 v[34:37], v[184:187], v[200:203], v[34:37]
	v_mfma_f32_16x16x32_bf16 v[22:25], v[176:179], v[216:219], v[22:25]
	v_mfma_f32_16x16x32_bf16 v[18:21], v[184:187], v[216:219], v[18:21]
	v_mfma_f32_16x16x32_bf16 v[6:9], v[176:179], v[224:227], v[6:9]
	v_mfma_f32_16x16x32_bf16 v[2:5], v[184:187], v[224:227], v[2:5]
	s_barrier
	s_add_i32 s27, 0, 0x18000
	v_add_u32_e32 v149, s27, v146
	s_add_i32 s28, 0, 0x1c000
	ds_read_b128 v[140:143], v149
	ds_read_b128 v[150:153], v149 offset:1024
	ds_read_b128 v[154:157], v149 offset:2048
	ds_read_b128 v[168:171], v149 offset:3072
	v_add_u32_e32 v149, s28, v146
	ds_read_b128 v[172:175], v149
	ds_read_b128 v[176:179], v149 offset:1024
	ds_read_b128 v[180:183], v149 offset:2048
	ds_read_b128 v[184:187], v149 offset:3072
	s_add_u32 s0, s68, 0x158000
	s_addc_u32 s1, s69, 0
	s_mov_b32 m0, s71
	v_lshl_add_u64 v[234:235], s[0:1], 0, v[130:131]
	ds_read_b128 v[188:191], v148 offset:32768
	ds_read_b128 v[192:195], v148 offset:33792
	ds_read_b128 v[196:199], v148 offset:34816
	ds_read_b128 v[200:203], v148 offset:35840
	ds_read_b128 v[204:207], v148 offset:36864
	ds_read_b128 v[216:219], v148 offset:37888
	ds_read_b128 v[220:223], v148 offset:38912
	ds_read_b128 v[224:227], v148 offset:39936
	global_load_lds_dwordx4 v[234:235], off
	v_lshl_add_u64 v[234:235], s[0:1], 0, v[132:133]
	s_mov_b32 m0, s72
	s_nop 0
	global_load_lds_dwordx4 v[234:235], off
	s_waitcnt vmcnt(8)
	s_waitcnt lgkmcnt(0)
	s_barrier
	s_waitcnt lgkmcnt(0)
	v_mfma_f32_16x16x32_bf16 v[126:129], v[140:143], v[188:191], v[126:129]
	v_mfma_f32_16x16x32_bf16 v[122:125], v[154:157], v[188:191], v[122:125]
	v_mfma_f32_16x16x32_bf16 v[110:113], v[140:143], v[196:199], v[110:113]
	v_mfma_f32_16x16x32_bf16 v[106:109], v[154:157], v[196:199], v[106:109]
	v_mfma_f32_16x16x32_bf16 v[94:97], v[140:143], v[204:207], v[94:97]
	v_mfma_f32_16x16x32_bf16 v[90:93], v[154:157], v[204:207], v[90:93]
	v_mfma_f32_16x16x32_bf16 v[78:81], v[140:143], v[220:223], v[78:81]
	v_mfma_f32_16x16x32_bf16 v[74:77], v[154:157], v[220:223], v[74:77]
	v_mfma_f32_16x16x32_bf16 v[126:129], v[150:153], v[192:195], v[126:129]
	v_mfma_f32_16x16x32_bf16 v[122:125], v[168:171], v[192:195], v[122:125]
	v_mfma_f32_16x16x32_bf16 v[110:113], v[150:153], v[200:203], v[110:113]
	v_mfma_f32_16x16x32_bf16 v[106:109], v[168:171], v[200:203], v[106:109]
	v_mfma_f32_16x16x32_bf16 v[94:97], v[150:153], v[216:219], v[94:97]
	v_mfma_f32_16x16x32_bf16 v[90:93], v[168:171], v[216:219], v[90:93]
	v_mfma_f32_16x16x32_bf16 v[78:81], v[150:153], v[224:227], v[78:81]
	v_mfma_f32_16x16x32_bf16 v[74:77], v[168:171], v[224:227], v[74:77]
	v_mfma_f32_16x16x32_bf16 v[118:121], v[172:175], v[188:191], v[118:121]
	v_mfma_f32_16x16x32_bf16 v[114:117], v[180:183], v[188:191], v[114:117]
	v_mfma_f32_16x16x32_bf16 v[102:105], v[172:175], v[196:199], v[102:105]
	v_mfma_f32_16x16x32_bf16 v[98:101], v[180:183], v[196:199], v[98:101]
	v_mfma_f32_16x16x32_bf16 v[86:89], v[172:175], v[204:207], v[86:89]
	v_mfma_f32_16x16x32_bf16 v[82:85], v[180:183], v[204:207], v[82:85]
	v_mfma_f32_16x16x32_bf16 v[70:73], v[172:175], v[220:223], v[70:73]
	v_mfma_f32_16x16x32_bf16 v[66:69], v[180:183], v[220:223], v[66:69]
	v_mfma_f32_16x16x32_bf16 v[118:121], v[176:179], v[192:195], v[118:121]
	v_mfma_f32_16x16x32_bf16 v[114:117], v[184:187], v[192:195], v[114:117]
	v_mfma_f32_16x16x32_bf16 v[102:105], v[176:179], v[200:203], v[102:105]
	v_mfma_f32_16x16x32_bf16 v[98:101], v[184:187], v[200:203], v[98:101]
	v_mfma_f32_16x16x32_bf16 v[86:89], v[176:179], v[216:219], v[86:89]
	v_mfma_f32_16x16x32_bf16 v[82:85], v[184:187], v[216:219], v[82:85]
	v_mfma_f32_16x16x32_bf16 v[70:73], v[176:179], v[224:227], v[70:73]
	v_mfma_f32_16x16x32_bf16 v[66:69], v[184:187], v[224:227], v[66:69]
	s_barrier
	s_add_i32 s0, s27, s58
	v_lshl_add_u64 v[144:145], v[144:145], 0, s[56:57]
	s_mov_b32 m0, s0
	ds_read_b128 v[188:191], v148 offset:49152
	ds_read_b128 v[192:195], v148 offset:50176
	ds_read_b128 v[196:199], v148 offset:51200
	ds_read_b128 v[200:203], v148 offset:52224
	ds_read_b128 v[204:207], v148 offset:53248
	ds_read_b128 v[216:219], v148 offset:54272
	ds_read_b128 v[220:223], v148 offset:55296
	ds_read_b128 v[224:227], v148 offset:56320
	global_load_lds_dwordx4 v[144:145], off
	s_add_i32 m0, s0, 0x2000
	s_add_u32 s0, s14, 0x158080
	v_lshl_add_u64 v[144:145], v[228:229], 0, s[56:57]
	s_addc_u32 s1, s15, 0
	s_add_i32 s14, s28, s58
	global_load_lds_dwordx4 v[144:145], off
	v_lshl_add_u64 v[144:145], s[0:1], 0, v[158:159]
	s_mov_b32 m0, s14
	s_nop 0
	global_load_lds_dwordx4 v[144:145], off
	v_lshl_add_u64 v[144:145], s[0:1], 0, v[134:135]
	s_add_i32 m0, s14, 0x2000
	s_nop 0
	global_load_lds_dwordx4 v[144:145], off
	v_lshl_add_u64 v[144:145], v[230:231], 0, s[56:57]
	s_mov_b32 m0, s73
	s_nop 0
	global_load_lds_dwordx4 v[144:145], off
	v_lshl_add_u64 v[144:145], v[232:233], 0, s[56:57]
	s_mov_b32 m0, s74
	s_nop 0
	global_load_lds_dwordx4 v[144:145], off
	s_waitcnt vmcnt(8)
	s_waitcnt lgkmcnt(0)
	s_barrier
	s_waitcnt lgkmcnt(0)
	v_mfma_f32_16x16x32_bf16 v[62:65], v[140:143], v[188:191], v[62:65]
	v_mfma_f32_16x16x32_bf16 v[58:61], v[154:157], v[188:191], v[58:61]
	v_mfma_f32_16x16x32_bf16 v[46:49], v[140:143], v[196:199], v[46:49]
	v_mfma_f32_16x16x32_bf16 v[42:45], v[154:157], v[196:199], v[42:45]
	v_mfma_f32_16x16x32_bf16 v[30:33], v[140:143], v[204:207], v[30:33]
	v_mfma_f32_16x16x32_bf16 v[26:29], v[154:157], v[204:207], v[26:29]
	v_mfma_f32_16x16x32_bf16 v[14:17], v[140:143], v[220:223], v[14:17]
	v_mfma_f32_16x16x32_bf16 v[10:13], v[154:157], v[220:223], v[10:13]
	v_mfma_f32_16x16x32_bf16 v[62:65], v[150:153], v[192:195], v[62:65]
	v_mfma_f32_16x16x32_bf16 v[58:61], v[168:171], v[192:195], v[58:61]
	v_mfma_f32_16x16x32_bf16 v[46:49], v[150:153], v[200:203], v[46:49]
	v_mfma_f32_16x16x32_bf16 v[42:45], v[168:171], v[200:203], v[42:45]
	v_mfma_f32_16x16x32_bf16 v[30:33], v[150:153], v[216:219], v[30:33]
	v_mfma_f32_16x16x32_bf16 v[26:29], v[168:171], v[216:219], v[26:29]
	v_mfma_f32_16x16x32_bf16 v[14:17], v[150:153], v[224:227], v[14:17]
	v_mfma_f32_16x16x32_bf16 v[10:13], v[168:171], v[224:227], v[10:13]
	v_mfma_f32_16x16x32_bf16 v[54:57], v[172:175], v[188:191], v[54:57]
	v_mfma_f32_16x16x32_bf16 v[50:53], v[180:183], v[188:191], v[50:53]
	v_mfma_f32_16x16x32_bf16 v[38:41], v[172:175], v[196:199], v[38:41]
	v_mfma_f32_16x16x32_bf16 v[34:37], v[180:183], v[196:199], v[34:37]
	v_mfma_f32_16x16x32_bf16 v[22:25], v[172:175], v[204:207], v[22:25]
	v_mfma_f32_16x16x32_bf16 v[18:21], v[180:183], v[204:207], v[18:21]
	v_mfma_f32_16x16x32_bf16 v[6:9], v[172:175], v[220:223], v[6:9]
	v_mfma_f32_16x16x32_bf16 v[2:5], v[180:183], v[220:223], v[2:5]
	v_mfma_f32_16x16x32_bf16 v[54:57], v[176:179], v[192:195], v[54:57]
	v_mfma_f32_16x16x32_bf16 v[50:53], v[184:187], v[192:195], v[50:53]
	v_mfma_f32_16x16x32_bf16 v[38:41], v[176:179], v[200:203], v[38:41]
	v_mfma_f32_16x16x32_bf16 v[34:37], v[184:187], v[200:203], v[34:37]
	v_mfma_f32_16x16x32_bf16 v[22:25], v[176:179], v[216:219], v[22:25]
	v_mfma_f32_16x16x32_bf16 v[18:21], v[184:187], v[216:219], v[18:21]
	v_mfma_f32_16x16x32_bf16 v[6:9], v[176:179], v[224:227], v[6:9]
	v_mfma_f32_16x16x32_bf16 v[2:5], v[184:187], v[224:227], v[2:5]
	s_barrier
	s_add_i32 s26, s26, 2
	s_add_u32 s24, s24, 0x100
	s_addc_u32 s25, s25, 0
	s_cmpk_gt_u32 s26, 0x53
	s_mov_b64 s[0:1], s[36:37]
	s_cbranch_scc0 .LBB0_353
	s_and_b64 vcc, exec, s[12:13]
	s_cbranch_vccz .LBB0_356
	s_barrier

.LBB0_388:
	v_readlane_b32 s0, v240, 63
	s_add_i32 s10, s0, 2
	s_cmp_lt_i32 s10, s93
	s_cselect_b64 s[0:1], -1, 0
	s_and_b64 s[12:13], s[20:21], s[0:1]
	v_readlane_b32 s34, v241, 13
	s_andn2_b64 vcc, exec, s[12:13]
	v_readlane_b32 s35, v241, 14
	s_cbranch_vccnz .LBB0_439
	s_setprio 0
	s_waitcnt vmcnt(0)
	s_waitcnt vmcnt(0) lgkmcnt(0)
	s_barrier
	s_mov_b64 s[12:13], exec
	v_readlane_b32 s14, v241, 3
	v_readlane_b32 s15, v241, 4
	s_and_b64 s[14:15], s[12:13], s[14:15]
	s_mov_b64 exec, s[14:15]
	s_cbranch_execz .LBB0_438
	v_mov_b32_e32 v1, s97
	s_waitcnt vmcnt(0) expcnt(0) lgkmcnt(0)
	ds_read_b32 v3, v1
	ds_read_b32 v2, v1 offset:4
	s_waitcnt lgkmcnt(1)
	v_cmp_ne_u32_e32 vcc, 0, v3
	s_cbranch_vccnz .LBB0_405
	v_readlane_b32 s16, v244, 0
	v_readlane_b32 s17, v244, 1
	s_load_dwordx2 s[14:15], s[16:17], 0x4
	s_mov_b32 s22, 1
	s_waitcnt lgkmcnt(0)
	s_mul_i32 s11, s14, s96
	s_mul_i32 s11, s11, s15
	s_branch .LBB0_393

.LBB0_487:
	v_readlane_b32 s0, v240, 63
	s_add_i32 s0, s0, 3
	s_cmp_lt_i32 s0, s93
	v_writelane_b32 v240, s0, 63
	s_cselect_b64 s[0:1], -1, 0
	s_and_b64 s[0:1], s[12:13], s[0:1]
	s_andn2_b64 vcc, exec, s[0:1]
	s_cbranch_vccnz .LBB0_537
	s_setprio 0
	s_waitcnt vmcnt(0)
	s_waitcnt vmcnt(0) lgkmcnt(0)
	s_barrier
	s_mov_b64 s[0:1], exec
	v_readlane_b32 s8, v241, 3
	v_readlane_b32 s9, v241, 4
	s_and_b64 s[8:9], s[0:1], s[8:9]
	s_mov_b64 exec, s[8:9]
	s_cbranch_execz .LBB0_536
	v_mov_b32_e32 v1, s97
	s_waitcnt vmcnt(0) expcnt(0) lgkmcnt(0)
	ds_read_b32 v3, v1
	ds_read_b32 v2, v1 offset:4
	s_waitcnt lgkmcnt(1)
	v_cmp_ne_u32_e32 vcc, 0, v3
	s_cbranch_vccnz .LBB0_504
	v_readlane_b32 s10, v244, 0
	v_readlane_b32 s11, v244, 1
	s_load_dwordx2 s[8:9], s[10:11], 0x4
	s_mov_b32 s10, 1
	s_waitcnt lgkmcnt(0)
	s_mul_i32 s3, s8, s96
	s_mul_i32 s3, s3, s9
	s_branch .LBB0_492

.LBB0_653:
	v_readlane_b32 s0, v240, 63
	s_add_i32 s3, s0, 1
	s_cmp_lt_i32 s3, s93
	s_cselect_b64 s[0:1], -1, 0
	s_and_b64 s[8:9], s[44:45], s[0:1]
	s_andn2_b64 vcc, exec, s[8:9]
	s_mov_b32 s26, s46
	s_cbranch_vccnz .LBB0_703
	s_setprio 0
	s_waitcnt vmcnt(0)
	s_waitcnt vmcnt(0) lgkmcnt(0)
	s_barrier
	s_mov_b64 s[8:9], exec
	v_readlane_b32 s10, v241, 3
	v_readlane_b32 s11, v241, 4
	s_and_b64 s[10:11], s[8:9], s[10:11]
	s_mov_b64 exec, s[10:11]
	s_cbranch_execz .LBB0_702
	v_mov_b32_e32 v1, s97
	s_waitcnt vmcnt(0) expcnt(0) lgkmcnt(0)
	ds_read_b32 v3, v1
	ds_read_b32 v2, v1 offset:4
	s_waitcnt lgkmcnt(1)
	v_cmp_ne_u32_e32 vcc, 0, v3
	s_cbranch_vccnz .LBB0_670
	v_readlane_b32 s12, v244, 0
	v_readlane_b32 s13, v244, 1
	s_load_dwordx2 s[10:11], s[12:13], 0x4
	s_waitcnt lgkmcnt(0)
	s_mul_i32 s10, s10, s96
	s_mul_i32 s10, s10, s11
	s_mov_b32 s11, 1
	s_branch .LBB0_658

.LBB0_715:
	s_cmp_lg_u64 s[22:23], 0
	s_cbranch_scc0 .Lsp_LBB0715
	s_setprio 1
.Lsp_LBB0715:
	s_add_u32 s14, s66, 0xfff80080
	s_addc_u32 s15, s67, -1
	s_add_i32 s24, 0, 0x10000
	s_cmp_eq_u32 s17, 28
	s_cselect_b32 s69, s49, s15
	s_cselect_b32 s68, s48, s14
	v_add_u32_e32 v147, s24, v144
	s_cselect_b32 s15, s1, s16
	s_cselect_b32 s14, s10, s11
	s_add_i32 s26, 0, 0x14000
	ds_read_b128 v[140:143], v147
	ds_read_b128 v[148:151], v147 offset:1024
	ds_read_b128 v[152:155], v147 offset:2048
	ds_read_b128 v[168:171], v147 offset:3072
	v_add_u32_e32 v147, s26, v144
	ds_read_b128 v[172:175], v147
	ds_read_b128 v[176:179], v147 offset:1024
	ds_read_b128 v[180:183], v147 offset:2048
	ds_read_b128 v[184:187], v147 offset:3072
	v_lshl_add_u64 v[156:157], s[66:67], 0, v[136:137]
	s_add_i32 m0, s65, 0xc000
	ds_read_b128 v[188:191], v146
	ds_read_b128 v[192:195], v146 offset:1024
	ds_read_b128 v[196:199], v146 offset:2048
	ds_read_b128 v[200:203], v146 offset:3072
	ds_read_b128 v[204:207], v146 offset:4096
	ds_read_b128 v[216:219], v146 offset:5120
	ds_read_b128 v[220:223], v146 offset:6144
	ds_read_b128 v[224:227], v146 offset:7168
	global_load_lds_dwordx4 v[156:157], off
	v_lshl_add_u64 v[156:157], s[66:67], 0, v[138:139]
	s_add_i32 m0, s65, 0xe000
	s_nop 0
	global_load_lds_dwordx4 v[156:157], off
	s_waitcnt vmcnt(8)
	s_waitcnt lgkmcnt(0)
	s_barrier
	s_waitcnt lgkmcnt(0)
	v_mfma_f32_16x16x32_bf16 v[126:129], v[140:143], v[188:191], v[126:129]
	v_mfma_f32_16x16x32_bf16 v[118:121], v[152:155], v[188:191], v[118:121]
	v_mfma_f32_16x16x32_bf16 v[106:109], v[140:143], v[196:199], v[106:109]
	v_mfma_f32_16x16x32_bf16 v[98:101], v[152:155], v[196:199], v[98:101]
	v_mfma_f32_16x16x32_bf16 v[90:93], v[140:143], v[204:207], v[90:93]
	v_mfma_f32_16x16x32_bf16 v[82:85], v[152:155], v[204:207], v[82:85]
	v_mfma_f32_16x16x32_bf16 v[74:77], v[140:143], v[220:223], v[74:77]
	v_mfma_f32_16x16x32_bf16 v[66:69], v[152:155], v[220:223], v[66:69]
	v_mfma_f32_16x16x32_bf16 v[126:129], v[148:151], v[192:195], v[126:129]
	v_mfma_f32_16x16x32_bf16 v[118:121], v[168:171], v[192:195], v[118:121]
	v_mfma_f32_16x16x32_bf16 v[106:109], v[148:151], v[200:203], v[106:109]
	v_mfma_f32_16x16x32_bf16 v[98:101], v[168:171], v[200:203], v[98:101]
	v_mfma_f32_16x16x32_bf16 v[90:93], v[148:151], v[216:219], v[90:93]
	v_mfma_f32_16x16x32_bf16 v[82:85], v[168:171], v[216:219], v[82:85]
	v_mfma_f32_16x16x32_bf16 v[74:77], v[148:151], v[224:227], v[74:77]
	v_mfma_f32_16x16x32_bf16 v[66:69], v[168:171], v[224:227], v[66:69]
	v_mfma_f32_16x16x32_bf16 v[122:125], v[172:175], v[188:191], v[122:125]
	v_mfma_f32_16x16x32_bf16 v[114:117], v[180:183], v[188:191], v[114:117]
	v_mfma_f32_16x16x32_bf16 v[110:113], v[172:175], v[196:199], v[110:113]
	v_mfma_f32_16x16x32_bf16 v[102:105], v[180:183], v[196:199], v[102:105]
	v_mfma_f32_16x16x32_bf16 v[94:97], v[172:175], v[204:207], v[94:97]
	v_mfma_f32_16x16x32_bf16 v[86:89], v[180:183], v[204:207], v[86:89]
	v_mfma_f32_16x16x32_bf16 v[78:81], v[172:175], v[220:223], v[78:81]
	v_mfma_f32_16x16x32_bf16 v[70:73], v[180:183], v[220:223], v[70:73]
	v_mfma_f32_16x16x32_bf16 v[122:125], v[176:179], v[192:195], v[122:125]
	v_mfma_f32_16x16x32_bf16 v[114:117], v[184:187], v[192:195], v[114:117]
	v_mfma_f32_16x16x32_bf16 v[110:113], v[176:179], v[200:203], v[110:113]
	v_mfma_f32_16x16x32_bf16 v[102:105], v[184:187], v[200:203], v[102:105]
	v_mfma_f32_16x16x32_bf16 v[94:97], v[176:179], v[216:219], v[94:97]
	v_mfma_f32_16x16x32_bf16 v[86:89], v[184:187], v[216:219], v[86:89]
	v_mfma_f32_16x16x32_bf16 v[78:81], v[176:179], v[224:227], v[78:81]
	v_mfma_f32_16x16x32_bf16 v[70:73], v[184:187], v[224:227], v[70:73]
	s_barrier
	s_add_i32 s24, s24, s59
	v_lshl_add_u64 v[156:157], s[14:15], 0, v[158:159]
	s_mov_b32 m0, s24
	ds_read_b128 v[188:191], v146 offset:16384
	ds_read_b128 v[192:195], v146 offset:17408
	ds_read_b128 v[196:199], v146 offset:18432
	ds_read_b128 v[200:203], v146 offset:19456
	ds_read_b128 v[204:207], v146 offset:20480
	ds_read_b128 v[216:219], v146 offset:21504
	ds_read_b128 v[220:223], v146 offset:22528
	ds_read_b128 v[224:227], v146 offset:23552
	global_load_lds_dwordx4 v[156:157], off
	s_add_i32 m0, s24, 0x2000
	s_add_u32 s24, s14, 0x80000
	v_lshl_add_u64 v[228:229], s[14:15], 0, v[134:135]
	s_addc_u32 s25, s15, 0
	s_add_i32 s26, s26, s59
	global_load_lds_dwordx4 v[228:229], off
	v_lshl_add_u64 v[230:231], s[24:25], 0, v[158:159]
	s_mov_b32 m0, s26
	v_lshl_add_u64 v[232:233], s[68:69], 0, v[132:133]
	global_load_lds_dwordx4 v[230:231], off
	v_lshl_add_u64 v[230:231], s[24:25], 0, v[134:135]
	s_add_i32 m0, s26, 0x2000
	s_nop 0
	global_load_lds_dwordx4 v[230:231], off
	v_lshl_add_u64 v[230:231], s[68:69], 0, v[130:131]
	s_mov_b32 m0, s65
	s_nop 0
	global_load_lds_dwordx4 v[230:231], off
	s_mov_b32 m0, s70
	s_nop 0
	global_load_lds_dwordx4 v[232:233], off
	s_waitcnt vmcnt(8)
	s_waitcnt lgkmcnt(0)
	s_barrier
	s_waitcnt lgkmcnt(0)
	v_mfma_f32_16x16x32_bf16 v[58:61], v[140:143], v[188:191], v[58:61]
	v_mfma_f32_16x16x32_bf16 v[50:53], v[152:155], v[188:191], v[50:53]
	v_mfma_f32_16x16x32_bf16 v[42:45], v[140:143], v[196:199], v[42:45]
	v_mfma_f32_16x16x32_bf16 v[34:37], v[152:155], v[196:199], v[34:37]
	v_mfma_f32_16x16x32_bf16 v[26:29], v[140:143], v[204:207], v[26:29]
	v_mfma_f32_16x16x32_bf16 v[18:21], v[152:155], v[204:207], v[18:21]
	v_mfma_f32_16x16x32_bf16 v[10:13], v[140:143], v[220:223], v[10:13]
	v_mfma_f32_16x16x32_bf16 v[2:5], v[152:155], v[220:223], v[2:5]
	v_mfma_f32_16x16x32_bf16 v[58:61], v[148:151], v[192:195], v[58:61]
	v_mfma_f32_16x16x32_bf16 v[50:53], v[168:171], v[192:195], v[50:53]
	v_mfma_f32_16x16x32_bf16 v[42:45], v[148:151], v[200:203], v[42:45]
	v_mfma_f32_16x16x32_bf16 v[34:37], v[168:171], v[200:203], v[34:37]
	v_mfma_f32_16x16x32_bf16 v[26:29], v[148:151], v[216:219], v[26:29]
	v_mfma_f32_16x16x32_bf16 v[18:21], v[168:171], v[216:219], v[18:21]
	v_mfma_f32_16x16x32_bf16 v[10:13], v[148:151], v[224:227], v[10:13]
	v_mfma_f32_16x16x32_bf16 v[2:5], v[168:171], v[224:227], v[2:5]
	v_mfma_f32_16x16x32_bf16 v[62:65], v[172:175], v[188:191], v[62:65]
	v_mfma_f32_16x16x32_bf16 v[54:57], v[180:183], v[188:191], v[54:57]
	v_mfma_f32_16x16x32_bf16 v[46:49], v[172:175], v[196:199], v[46:49]
	v_mfma_f32_16x16x32_bf16 v[38:41], v[180:183], v[196:199], v[38:41]
	v_mfma_f32_16x16x32_bf16 v[30:33], v[172:175], v[204:207], v[30:33]
	v_mfma_f32_16x16x32_bf16 v[22:25], v[180:183], v[204:207], v[22:25]
	v_mfma_f32_16x16x32_bf16 v[14:17], v[172:175], v[220:223], v[14:17]
	v_mfma_f32_16x16x32_bf16 v[6:9], v[180:183], v[220:223], v[6:9]
	v_mfma_f32_16x16x32_bf16 v[62:65], v[176:179], v[192:195], v[62:65]
	v_mfma_f32_16x16x32_bf16 v[54:57], v[184:187], v[192:195], v[54:57]
	v_mfma_f32_16x16x32_bf16 v[46:49], v[176:179], v[200:203], v[46:49]
	v_mfma_f32_16x16x32_bf16 v[38:41], v[184:187], v[200:203], v[38:41]
	v_mfma_f32_16x16x32_bf16 v[30:33], v[176:179], v[216:219], v[30:33]
	v_mfma_f32_16x16x32_bf16 v[22:25], v[184:187], v[216:219], v[22:25]
	v_mfma_f32_16x16x32_bf16 v[14:17], v[176:179], v[224:227], v[14:17]
	v_mfma_f32_16x16x32_bf16 v[6:9], v[184:187], v[224:227], v[6:9]
	s_barrier
	s_add_i32 s26, 0, 0x18000
	v_add_u32_e32 v147, s26, v144
	s_add_i32 s27, 0, 0x1c000
	ds_read_b128 v[140:143], v147
	ds_read_b128 v[148:151], v147 offset:1024
	ds_read_b128 v[152:155], v147 offset:2048
	ds_read_b128 v[168:171], v147 offset:3072
	v_add_u32_e32 v147, s27, v144
	ds_read_b128 v[172:175], v147
	ds_read_b128 v[176:179], v147 offset:1024
	ds_read_b128 v[180:183], v147 offset:2048
	ds_read_b128 v[184:187], v147 offset:3072
	s_add_u32 s24, s68, 0x80000
	s_addc_u32 s25, s69, 0
	s_mov_b32 m0, s71
	v_lshl_add_u64 v[234:235], s[24:25], 0, v[130:131]
	ds_read_b128 v[188:191], v146 offset:32768
	ds_read_b128 v[192:195], v146 offset:33792
	ds_read_b128 v[196:199], v146 offset:34816
	ds_read_b128 v[200:203], v146 offset:35840
	ds_read_b128 v[204:207], v146 offset:36864
	ds_read_b128 v[216:219], v146 offset:37888
	ds_read_b128 v[220:223], v146 offset:38912
	ds_read_b128 v[224:227], v146 offset:39936
	global_load_lds_dwordx4 v[234:235], off
	v_lshl_add_u64 v[234:235], s[24:25], 0, v[132:133]
	s_mov_b32 m0, s72
	s_nop 0
	global_load_lds_dwordx4 v[234:235], off
	s_waitcnt vmcnt(8)
	s_waitcnt lgkmcnt(0)
	s_barrier
	s_waitcnt lgkmcnt(0)
	v_mfma_f32_16x16x32_bf16 v[126:129], v[140:143], v[188:191], v[126:129]
	v_mfma_f32_16x16x32_bf16 v[118:121], v[152:155], v[188:191], v[118:121]
	v_mfma_f32_16x16x32_bf16 v[106:109], v[140:143], v[196:199], v[106:109]
	v_mfma_f32_16x16x32_bf16 v[98:101], v[152:155], v[196:199], v[98:101]
	v_mfma_f32_16x16x32_bf16 v[90:93], v[140:143], v[204:207], v[90:93]
	v_mfma_f32_16x16x32_bf16 v[82:85], v[152:155], v[204:207], v[82:85]
	v_mfma_f32_16x16x32_bf16 v[74:77], v[140:143], v[220:223], v[74:77]
	v_mfma_f32_16x16x32_bf16 v[66:69], v[152:155], v[220:223], v[66:69]
	v_mfma_f32_16x16x32_bf16 v[126:129], v[148:151], v[192:195], v[126:129]
	v_mfma_f32_16x16x32_bf16 v[118:121], v[168:171], v[192:195], v[118:121]
	v_mfma_f32_16x16x32_bf16 v[106:109], v[148:151], v[200:203], v[106:109]
	v_mfma_f32_16x16x32_bf16 v[98:101], v[168:171], v[200:203], v[98:101]
	v_mfma_f32_16x16x32_bf16 v[90:93], v[148:151], v[216:219], v[90:93]
	v_mfma_f32_16x16x32_bf16 v[82:85], v[168:171], v[216:219], v[82:85]
	v_mfma_f32_16x16x32_bf16 v[74:77], v[148:151], v[224:227], v[74:77]
	v_mfma_f32_16x16x32_bf16 v[66:69], v[168:171], v[224:227], v[66:69]
	v_mfma_f32_16x16x32_bf16 v[122:125], v[172:175], v[188:191], v[122:125]
	v_mfma_f32_16x16x32_bf16 v[114:117], v[180:183], v[188:191], v[114:117]
	v_mfma_f32_16x16x32_bf16 v[110:113], v[172:175], v[196:199], v[110:113]
	v_mfma_f32_16x16x32_bf16 v[102:105], v[180:183], v[196:199], v[102:105]
	v_mfma_f32_16x16x32_bf16 v[94:97], v[172:175], v[204:207], v[94:97]
	v_mfma_f32_16x16x32_bf16 v[86:89], v[180:183], v[204:207], v[86:89]
	v_mfma_f32_16x16x32_bf16 v[78:81], v[172:175], v[220:223], v[78:81]
	v_mfma_f32_16x16x32_bf16 v[70:73], v[180:183], v[220:223], v[70:73]
	v_mfma_f32_16x16x32_bf16 v[122:125], v[176:179], v[192:195], v[122:125]
	v_mfma_f32_16x16x32_bf16 v[114:117], v[184:187], v[192:195], v[114:117]
	v_mfma_f32_16x16x32_bf16 v[110:113], v[176:179], v[200:203], v[110:113]
	v_mfma_f32_16x16x32_bf16 v[102:105], v[184:187], v[200:203], v[102:105]
	v_mfma_f32_16x16x32_bf16 v[94:97], v[176:179], v[216:219], v[94:97]
	v_mfma_f32_16x16x32_bf16 v[86:89], v[184:187], v[216:219], v[86:89]
	v_mfma_f32_16x16x32_bf16 v[78:81], v[176:179], v[224:227], v[78:81]
	v_mfma_f32_16x16x32_bf16 v[70:73], v[184:187], v[224:227], v[70:73]
	s_barrier
	s_add_i32 s24, s26, s59
	v_lshl_add_u64 v[156:157], v[156:157], 0, s[56:57]
	s_mov_b32 m0, s24
	ds_read_b128 v[188:191], v146 offset:49152
	ds_read_b128 v[192:195], v146 offset:50176
	ds_read_b128 v[196:199], v146 offset:51200
	ds_read_b128 v[200:203], v146 offset:52224
	ds_read_b128 v[204:207], v146 offset:53248
	ds_read_b128 v[216:219], v146 offset:54272
	ds_read_b128 v[220:223], v146 offset:55296
	ds_read_b128 v[224:227], v146 offset:56320
	global_load_lds_dwordx4 v[156:157], off
	s_add_i32 m0, s24, 0x2000
	s_add_u32 s14, s14, 0x80080
	v_lshl_add_u64 v[156:157], v[228:229], 0, s[56:57]
	s_addc_u32 s15, s15, 0
	s_add_i32 s24, s27, s59
	global_load_lds_dwordx4 v[156:157], off
	v_lshl_add_u64 v[156:157], s[14:15], 0, v[158:159]
	s_mov_b32 m0, s24
	s_nop 0
	global_load_lds_dwordx4 v[156:157], off
	v_lshl_add_u64 v[156:157], s[14:15], 0, v[134:135]
	s_add_i32 m0, s24, 0x2000
	s_nop 0
	global_load_lds_dwordx4 v[156:157], off
	v_lshl_add_u64 v[156:157], v[230:231], 0, s[56:57]
	s_mov_b32 m0, s54
	s_nop 0
	global_load_lds_dwordx4 v[156:157], off
	v_lshl_add_u64 v[156:157], v[232:233], 0, s[56:57]
	s_mov_b32 m0, s73
	s_nop 0
	global_load_lds_dwordx4 v[156:157], off
	s_waitcnt vmcnt(8)
	s_waitcnt lgkmcnt(0)
	s_barrier
	s_waitcnt lgkmcnt(0)
	v_mfma_f32_16x16x32_bf16 v[58:61], v[140:143], v[188:191], v[58:61]
	v_mfma_f32_16x16x32_bf16 v[50:53], v[152:155], v[188:191], v[50:53]
	v_mfma_f32_16x16x32_bf16 v[42:45], v[140:143], v[196:199], v[42:45]
	v_mfma_f32_16x16x32_bf16 v[34:37], v[152:155], v[196:199], v[34:37]
	v_mfma_f32_16x16x32_bf16 v[26:29], v[140:143], v[204:207], v[26:29]
	v_mfma_f32_16x16x32_bf16 v[18:21], v[152:155], v[204:207], v[18:21]
	v_mfma_f32_16x16x32_bf16 v[10:13], v[140:143], v[220:223], v[10:13]
	v_mfma_f32_16x16x32_bf16 v[2:5], v[152:155], v[220:223], v[2:5]
	v_mfma_f32_16x16x32_bf16 v[58:61], v[148:151], v[192:195], v[58:61]
	v_mfma_f32_16x16x32_bf16 v[50:53], v[168:171], v[192:195], v[50:53]
	v_mfma_f32_16x16x32_bf16 v[42:45], v[148:151], v[200:203], v[42:45]
	v_mfma_f32_16x16x32_bf16 v[34:37], v[168:171], v[200:203], v[34:37]
	v_mfma_f32_16x16x32_bf16 v[26:29], v[148:151], v[216:219], v[26:29]
	v_mfma_f32_16x16x32_bf16 v[18:21], v[168:171], v[216:219], v[18:21]
	v_mfma_f32_16x16x32_bf16 v[10:13], v[148:151], v[224:227], v[10:13]
	v_mfma_f32_16x16x32_bf16 v[2:5], v[168:171], v[224:227], v[2:5]
	v_mfma_f32_16x16x32_bf16 v[62:65], v[172:175], v[188:191], v[62:65]
	v_mfma_f32_16x16x32_bf16 v[54:57], v[180:183], v[188:191], v[54:57]
	v_mfma_f32_16x16x32_bf16 v[46:49], v[172:175], v[196:199], v[46:49]
	v_mfma_f32_16x16x32_bf16 v[38:41], v[180:183], v[196:199], v[38:41]
	v_mfma_f32_16x16x32_bf16 v[30:33], v[172:175], v[204:207], v[30:33]
	v_mfma_f32_16x16x32_bf16 v[22:25], v[180:183], v[204:207], v[22:25]
	v_mfma_f32_16x16x32_bf16 v[14:17], v[172:175], v[220:223], v[14:17]
	v_mfma_f32_16x16x32_bf16 v[6:9], v[180:183], v[220:223], v[6:9]
	v_mfma_f32_16x16x32_bf16 v[62:65], v[176:179], v[192:195], v[62:65]
	v_mfma_f32_16x16x32_bf16 v[54:57], v[184:187], v[192:195], v[54:57]
	v_mfma_f32_16x16x32_bf16 v[46:49], v[176:179], v[200:203], v[46:49]
	v_mfma_f32_16x16x32_bf16 v[38:41], v[184:187], v[200:203], v[38:41]
	v_mfma_f32_16x16x32_bf16 v[30:33], v[176:179], v[216:219], v[30:33]
	v_mfma_f32_16x16x32_bf16 v[22:25], v[184:187], v[216:219], v[22:25]
	v_mfma_f32_16x16x32_bf16 v[14:17], v[176:179], v[224:227], v[14:17]
	v_mfma_f32_16x16x32_bf16 v[6:9], v[184:187], v[224:227], v[6:9]
	s_barrier
	s_add_i32 s17, s17, 2
	s_add_u32 s66, s66, 0x100
	s_addc_u32 s67, s67, 0
	s_add_u32 s11, s11, 0x100
	s_addc_u32 s16, s16, 0
	s_cmp_gt_u32 s17, 29
	s_cbranch_scc0 .LBB0_715
	s_and_b64 vcc, exec, s[22:23]
	s_cbranch_vccz .LBB0_718
	s_barrier

.LBB0_738:
	v_readlane_b32 s0, v240, 63
	s_add_i32 s3, s0, 2
	s_cmp_lt_i32 s3, s93
	s_cselect_b64 s[0:1], -1, 0
	s_and_b64 s[8:9], s[8:9], s[0:1]
	s_mov_b64 s[0:1], 0
	s_andn2_b64 vcc, exec, s[8:9]
	s_mov_b64 s[60:61], 0
	s_cbranch_vccnz .LBB0_788
	s_setprio 0
	s_waitcnt vmcnt(0)
	s_waitcnt vmcnt(0) lgkmcnt(0)
	s_barrier
	s_mov_b64 s[8:9], exec
	v_readlane_b32 s10, v241, 3
	v_readlane_b32 s11, v241, 4
	s_and_b64 s[10:11], s[8:9], s[10:11]
	s_mov_b64 exec, s[10:11]
	s_cbranch_execz .LBB0_787
	v_mov_b32_e32 v1, s97
	s_waitcnt vmcnt(0) expcnt(0) lgkmcnt(0)
	ds_read_b32 v3, v1
	ds_read_b32 v2, v1 offset:4
	s_waitcnt lgkmcnt(1)
	v_cmp_ne_u32_e32 vcc, 0, v3
	s_cbranch_vccnz .LBB0_755
	v_readlane_b32 s12, v244, 0
	v_readlane_b32 s13, v244, 1
	s_load_dwordx2 s[10:11], s[12:13], 0x4
	s_waitcnt lgkmcnt(0)
	s_mul_i32 s10, s10, s96
	s_mul_i32 s10, s10, s11
	s_mov_b32 s11, 1
	s_branch .LBB0_743

.LBB0_801:
	s_cmp_lg_u64 s[20:21], 0
	s_cbranch_scc0 .Lsp_LBB0801
	s_setprio 1
.Lsp_LBB0801:
	s_add_u32 s14, s50, 0xfff80080
	s_addc_u32 s15, s51, -1
	s_add_i32 s30, 0, 0x10000
	s_cmp_eq_u32 s29, 28
	s_cselect_b32 s65, s43, s15
	s_cselect_b32 s64, s42, s14
	v_add_u32_e32 v150, s30, v152
	s_cselect_b32 s15, s1, s23
	s_cselect_b32 s14, s16, s17
	s_add_i32 s34, 0, 0x14000
	ds_read_b128 v[142:145], v150
	ds_read_b128 v[146:149], v150 offset:1024
	ds_read_b128 v[168:171], v150 offset:2048
	ds_read_b128 v[172:175], v150 offset:3072
	v_add_u32_e32 v150, s34, v152
	ds_read_b128 v[176:179], v150
	ds_read_b128 v[180:183], v150 offset:1024
	ds_read_b128 v[184:187], v150 offset:2048
	ds_read_b128 v[188:191], v150 offset:3072
	v_lshl_add_u64 v[150:151], s[50:51], 0, v[138:139]
	s_add_i32 m0, s58, 0xc000
	ds_read_b128 v[192:195], v155
	ds_read_b128 v[196:199], v155 offset:1024
	ds_read_b128 v[200:203], v155 offset:2048
	ds_read_b128 v[204:207], v155 offset:3072
	ds_read_b128 v[216:219], v155 offset:4096
	ds_read_b128 v[220:223], v155 offset:5120
	ds_read_b128 v[224:227], v155 offset:6144
	ds_read_b128 v[228:231], v155 offset:7168
	global_load_lds_dwordx4 v[150:151], off
	v_lshl_add_u64 v[150:151], s[50:51], 0, v[140:141]
	s_add_i32 m0, s58, 0xe000
	s_nop 0
	global_load_lds_dwordx4 v[150:151], off
	s_waitcnt vmcnt(8)
	s_waitcnt lgkmcnt(0)
	s_barrier
	s_waitcnt lgkmcnt(0)
	v_mfma_f32_16x16x32_bf16 v[126:129], v[142:145], v[192:195], v[126:129]
	v_mfma_f32_16x16x32_bf16 v[122:125], v[168:171], v[192:195], v[122:125]
	v_mfma_f32_16x16x32_bf16 v[110:113], v[142:145], v[200:203], v[110:113]
	v_mfma_f32_16x16x32_bf16 v[106:109], v[168:171], v[200:203], v[106:109]
	v_mfma_f32_16x16x32_bf16 v[94:97], v[142:145], v[216:219], v[94:97]
	v_mfma_f32_16x16x32_bf16 v[90:93], v[168:171], v[216:219], v[90:93]
	v_mfma_f32_16x16x32_bf16 v[78:81], v[142:145], v[224:227], v[78:81]
	v_mfma_f32_16x16x32_bf16 v[74:77], v[168:171], v[224:227], v[74:77]
	v_mfma_f32_16x16x32_bf16 v[126:129], v[146:149], v[196:199], v[126:129]
	v_mfma_f32_16x16x32_bf16 v[122:125], v[172:175], v[196:199], v[122:125]
	v_mfma_f32_16x16x32_bf16 v[110:113], v[146:149], v[204:207], v[110:113]
	v_mfma_f32_16x16x32_bf16 v[106:109], v[172:175], v[204:207], v[106:109]
	v_mfma_f32_16x16x32_bf16 v[94:97], v[146:149], v[220:223], v[94:97]
	v_mfma_f32_16x16x32_bf16 v[90:93], v[172:175], v[220:223], v[90:93]
	v_mfma_f32_16x16x32_bf16 v[78:81], v[146:149], v[228:231], v[78:81]
	v_mfma_f32_16x16x32_bf16 v[74:77], v[172:175], v[228:231], v[74:77]
	v_mfma_f32_16x16x32_bf16 v[118:121], v[176:179], v[192:195], v[118:121]
	v_mfma_f32_16x16x32_bf16 v[114:117], v[184:187], v[192:195], v[114:117]
	v_mfma_f32_16x16x32_bf16 v[102:105], v[176:179], v[200:203], v[102:105]
	v_mfma_f32_16x16x32_bf16 v[98:101], v[184:187], v[200:203], v[98:101]
	v_mfma_f32_16x16x32_bf16 v[86:89], v[176:179], v[216:219], v[86:89]
	v_mfma_f32_16x16x32_bf16 v[82:85], v[184:187], v[216:219], v[82:85]
	v_mfma_f32_16x16x32_bf16 v[70:73], v[176:179], v[224:227], v[70:73]
	v_mfma_f32_16x16x32_bf16 v[66:69], v[184:187], v[224:227], v[66:69]
	v_mfma_f32_16x16x32_bf16 v[118:121], v[180:183], v[196:199], v[118:121]
	v_mfma_f32_16x16x32_bf16 v[114:117], v[188:191], v[196:199], v[114:117]
	v_mfma_f32_16x16x32_bf16 v[102:105], v[180:183], v[204:207], v[102:105]
	v_mfma_f32_16x16x32_bf16 v[98:101], v[188:191], v[204:207], v[98:101]
	v_mfma_f32_16x16x32_bf16 v[86:89], v[180:183], v[220:223], v[86:89]
	v_mfma_f32_16x16x32_bf16 v[82:85], v[188:191], v[220:223], v[82:85]
	v_mfma_f32_16x16x32_bf16 v[70:73], v[180:183], v[228:231], v[70:73]
	v_mfma_f32_16x16x32_bf16 v[66:69], v[188:191], v[228:231], v[66:69]
	s_barrier
	s_add_i32 s30, s30, s11
	v_lshl_add_u64 v[150:151], s[14:15], 0, v[158:159]
	s_mov_b32 m0, s30
	ds_read_b128 v[192:195], v155 offset:16384
	ds_read_b128 v[196:199], v155 offset:17408
	ds_read_b128 v[200:203], v155 offset:18432
	ds_read_b128 v[204:207], v155 offset:19456
	ds_read_b128 v[216:219], v155 offset:20480
	ds_read_b128 v[220:223], v155 offset:21504
	ds_read_b128 v[224:227], v155 offset:22528
	ds_read_b128 v[228:231], v155 offset:23552
	global_load_lds_dwordx4 v[150:151], off
	s_add_i32 m0, s30, 0x2000
	s_add_u32 s30, s14, 0x80000
	v_lshl_add_u64 v[156:157], s[14:15], 0, v[134:135]
	s_addc_u32 s31, s15, 0
	s_add_i32 s34, s34, s11
	global_load_lds_dwordx4 v[156:157], off
	v_lshl_add_u64 v[232:233], s[30:31], 0, v[158:159]
	s_mov_b32 m0, s34
	v_lshl_add_u64 v[234:235], s[64:65], 0, v[132:133]
	global_load_lds_dwordx4 v[232:233], off
	v_lshl_add_u64 v[232:233], s[30:31], 0, v[134:135]
	s_add_i32 m0, s34, 0x2000
	s_nop 0
	global_load_lds_dwordx4 v[232:233], off
	v_lshl_add_u64 v[232:233], s[64:65], 0, v[130:131]
	s_mov_b32 m0, s58
	s_nop 0
	global_load_lds_dwordx4 v[232:233], off
	s_mov_b32 m0, s24
	s_nop 0
	global_load_lds_dwordx4 v[234:235], off
	s_waitcnt vmcnt(8)
	s_waitcnt lgkmcnt(0)
	s_barrier
	s_waitcnt lgkmcnt(0)
	v_mfma_f32_16x16x32_bf16 v[62:65], v[142:145], v[192:195], v[62:65]
	v_mfma_f32_16x16x32_bf16 v[58:61], v[168:171], v[192:195], v[58:61]
	v_mfma_f32_16x16x32_bf16 v[46:49], v[142:145], v[200:203], v[46:49]
	v_mfma_f32_16x16x32_bf16 v[42:45], v[168:171], v[200:203], v[42:45]
	v_mfma_f32_16x16x32_bf16 v[30:33], v[142:145], v[216:219], v[30:33]
	v_mfma_f32_16x16x32_bf16 v[26:29], v[168:171], v[216:219], v[26:29]
	v_mfma_f32_16x16x32_bf16 v[14:17], v[142:145], v[224:227], v[14:17]
	v_mfma_f32_16x16x32_bf16 v[10:13], v[168:171], v[224:227], v[10:13]
	v_mfma_f32_16x16x32_bf16 v[62:65], v[146:149], v[196:199], v[62:65]
	v_mfma_f32_16x16x32_bf16 v[58:61], v[172:175], v[196:199], v[58:61]
	v_mfma_f32_16x16x32_bf16 v[46:49], v[146:149], v[204:207], v[46:49]
	v_mfma_f32_16x16x32_bf16 v[42:45], v[172:175], v[204:207], v[42:45]
	v_mfma_f32_16x16x32_bf16 v[30:33], v[146:149], v[220:223], v[30:33]
	v_mfma_f32_16x16x32_bf16 v[26:29], v[172:175], v[220:223], v[26:29]
	v_mfma_f32_16x16x32_bf16 v[14:17], v[146:149], v[228:231], v[14:17]
	v_mfma_f32_16x16x32_bf16 v[10:13], v[172:175], v[228:231], v[10:13]
	v_mfma_f32_16x16x32_bf16 v[54:57], v[176:179], v[192:195], v[54:57]
	v_mfma_f32_16x16x32_bf16 v[50:53], v[184:187], v[192:195], v[50:53]
	v_mfma_f32_16x16x32_bf16 v[38:41], v[176:179], v[200:203], v[38:41]
	v_mfma_f32_16x16x32_bf16 v[34:37], v[184:187], v[200:203], v[34:37]
	v_mfma_f32_16x16x32_bf16 v[22:25], v[176:179], v[216:219], v[22:25]
	v_mfma_f32_16x16x32_bf16 v[18:21], v[184:187], v[216:219], v[18:21]
	v_mfma_f32_16x16x32_bf16 v[6:9], v[176:179], v[224:227], v[6:9]
	v_mfma_f32_16x16x32_bf16 v[2:5], v[184:187], v[224:227], v[2:5]
	v_mfma_f32_16x16x32_bf16 v[54:57], v[180:183], v[196:199], v[54:57]
	v_mfma_f32_16x16x32_bf16 v[50:53], v[188:191], v[196:199], v[50:53]
	v_mfma_f32_16x16x32_bf16 v[38:41], v[180:183], v[204:207], v[38:41]
	v_mfma_f32_16x16x32_bf16 v[34:37], v[188:191], v[204:207], v[34:37]
	v_mfma_f32_16x16x32_bf16 v[22:25], v[180:183], v[220:223], v[22:25]
	v_mfma_f32_16x16x32_bf16 v[18:21], v[188:191], v[220:223], v[18:21]
	v_mfma_f32_16x16x32_bf16 v[6:9], v[180:183], v[228:231], v[6:9]
	v_mfma_f32_16x16x32_bf16 v[2:5], v[188:191], v[228:231], v[2:5]
	s_barrier
	s_add_i32 s34, 0, 0x18000
	v_add_u32_e32 v161, s34, v152
	s_add_i32 s35, 0, 0x1c000
	ds_read_b128 v[142:145], v161
	ds_read_b128 v[146:149], v161 offset:1024
	ds_read_b128 v[168:171], v161 offset:2048
	ds_read_b128 v[172:175], v161 offset:3072
	v_add_u32_e32 v161, s35, v152
	ds_read_b128 v[176:179], v161
	ds_read_b128 v[180:183], v161 offset:1024
	ds_read_b128 v[184:187], v161 offset:2048
	ds_read_b128 v[188:191], v161 offset:3072
	s_add_u32 s30, s64, 0x80000
	s_addc_u32 s31, s65, 0
	s_mov_b32 m0, s25
	v_lshl_add_u64 v[236:237], s[30:31], 0, v[130:131]
	ds_read_b128 v[192:195], v155 offset:32768
	ds_read_b128 v[196:199], v155 offset:33792
	ds_read_b128 v[200:203], v155 offset:34816
	ds_read_b128 v[204:207], v155 offset:35840
	ds_read_b128 v[216:219], v155 offset:36864
	ds_read_b128 v[220:223], v155 offset:37888
	ds_read_b128 v[224:227], v155 offset:38912
	ds_read_b128 v[228:231], v155 offset:39936
	global_load_lds_dwordx4 v[236:237], off
	v_lshl_add_u64 v[236:237], s[30:31], 0, v[132:133]
	s_mov_b32 m0, s59
	s_nop 0
	global_load_lds_dwordx4 v[236:237], off
	s_waitcnt vmcnt(8)
	s_waitcnt lgkmcnt(0)
	s_barrier
	s_waitcnt lgkmcnt(0)
	v_mfma_f32_16x16x32_bf16 v[126:129], v[142:145], v[192:195], v[126:129]
	v_mfma_f32_16x16x32_bf16 v[122:125], v[168:171], v[192:195], v[122:125]
	v_mfma_f32_16x16x32_bf16 v[110:113], v[142:145], v[200:203], v[110:113]
	v_mfma_f32_16x16x32_bf16 v[106:109], v[168:171], v[200:203], v[106:109]
	v_mfma_f32_16x16x32_bf16 v[94:97], v[142:145], v[216:219], v[94:97]
	v_mfma_f32_16x16x32_bf16 v[90:93], v[168:171], v[216:219], v[90:93]
	v_mfma_f32_16x16x32_bf16 v[78:81], v[142:145], v[224:227], v[78:81]
	v_mfma_f32_16x16x32_bf16 v[74:77], v[168:171], v[224:227], v[74:77]
	v_mfma_f32_16x16x32_bf16 v[126:129], v[146:149], v[196:199], v[126:129]
	v_mfma_f32_16x16x32_bf16 v[122:125], v[172:175], v[196:199], v[122:125]
	v_mfma_f32_16x16x32_bf16 v[110:113], v[146:149], v[204:207], v[110:113]
	v_mfma_f32_16x16x32_bf16 v[106:109], v[172:175], v[204:207], v[106:109]
	v_mfma_f32_16x16x32_bf16 v[94:97], v[146:149], v[220:223], v[94:97]
	v_mfma_f32_16x16x32_bf16 v[90:93], v[172:175], v[220:223], v[90:93]
	v_mfma_f32_16x16x32_bf16 v[78:81], v[146:149], v[228:231], v[78:81]
	v_mfma_f32_16x16x32_bf16 v[74:77], v[172:175], v[228:231], v[74:77]
	v_mfma_f32_16x16x32_bf16 v[118:121], v[176:179], v[192:195], v[118:121]
	v_mfma_f32_16x16x32_bf16 v[114:117], v[184:187], v[192:195], v[114:117]
	v_mfma_f32_16x16x32_bf16 v[102:105], v[176:179], v[200:203], v[102:105]
	v_mfma_f32_16x16x32_bf16 v[98:101], v[184:187], v[200:203], v[98:101]
	v_mfma_f32_16x16x32_bf16 v[86:89], v[176:179], v[216:219], v[86:89]
	v_mfma_f32_16x16x32_bf16 v[82:85], v[184:187], v[216:219], v[82:85]
	v_mfma_f32_16x16x32_bf16 v[70:73], v[176:179], v[224:227], v[70:73]
	v_mfma_f32_16x16x32_bf16 v[66:69], v[184:187], v[224:227], v[66:69]
	v_mfma_f32_16x16x32_bf16 v[118:121], v[180:183], v[196:199], v[118:121]
	v_mfma_f32_16x16x32_bf16 v[114:117], v[188:191], v[196:199], v[114:117]
	v_mfma_f32_16x16x32_bf16 v[102:105], v[180:183], v[204:207], v[102:105]
	v_mfma_f32_16x16x32_bf16 v[98:101], v[188:191], v[204:207], v[98:101]
	v_mfma_f32_16x16x32_bf16 v[86:89], v[180:183], v[220:223], v[86:89]
	v_mfma_f32_16x16x32_bf16 v[82:85], v[188:191], v[220:223], v[82:85]
	v_mfma_f32_16x16x32_bf16 v[70:73], v[180:183], v[228:231], v[70:73]
	v_mfma_f32_16x16x32_bf16 v[66:69], v[188:191], v[228:231], v[66:69]
	s_barrier
	s_add_i32 s30, s34, s11
	v_lshl_add_u64 v[150:151], v[150:151], 0, s[56:57]
	s_mov_b32 m0, s30
	ds_read_b128 v[192:195], v155 offset:49152
	ds_read_b128 v[196:199], v155 offset:50176
	ds_read_b128 v[200:203], v155 offset:51200
	ds_read_b128 v[204:207], v155 offset:52224
	ds_read_b128 v[216:219], v155 offset:53248
	ds_read_b128 v[220:223], v155 offset:54272
	ds_read_b128 v[224:227], v155 offset:55296
	ds_read_b128 v[228:231], v155 offset:56320
	global_load_lds_dwordx4 v[150:151], off
	s_add_i32 m0, s30, 0x2000
	s_add_u32 s14, s14, 0x80080
	v_lshl_add_u64 v[150:151], v[156:157], 0, s[56:57]
	s_addc_u32 s15, s15, 0
	s_add_i32 s30, s35, s11
	global_load_lds_dwordx4 v[150:151], off
	v_lshl_add_u64 v[150:151], s[14:15], 0, v[158:159]
	s_mov_b32 m0, s30
	s_nop 0
	global_load_lds_dwordx4 v[150:151], off
	v_lshl_add_u64 v[150:151], s[14:15], 0, v[134:135]
	s_add_i32 m0, s30, 0x2000
	s_nop 0
	global_load_lds_dwordx4 v[150:151], off
	v_lshl_add_u64 v[150:151], v[232:233], 0, s[56:57]
	s_mov_b32 m0, s26
	s_nop 0
	global_load_lds_dwordx4 v[150:151], off
	v_lshl_add_u64 v[150:151], v[234:235], 0, s[56:57]
	s_mov_b32 m0, s27
	s_nop 0
	global_load_lds_dwordx4 v[150:151], off
	s_waitcnt vmcnt(8)
	s_waitcnt lgkmcnt(0)
	s_barrier
	s_waitcnt lgkmcnt(0)
	v_mfma_f32_16x16x32_bf16 v[62:65], v[142:145], v[192:195], v[62:65]
	v_mfma_f32_16x16x32_bf16 v[58:61], v[168:171], v[192:195], v[58:61]
	v_mfma_f32_16x16x32_bf16 v[46:49], v[142:145], v[200:203], v[46:49]
	v_mfma_f32_16x16x32_bf16 v[42:45], v[168:171], v[200:203], v[42:45]
	v_mfma_f32_16x16x32_bf16 v[30:33], v[142:145], v[216:219], v[30:33]
	v_mfma_f32_16x16x32_bf16 v[26:29], v[168:171], v[216:219], v[26:29]
	v_mfma_f32_16x16x32_bf16 v[14:17], v[142:145], v[224:227], v[14:17]
	v_mfma_f32_16x16x32_bf16 v[10:13], v[168:171], v[224:227], v[10:13]
	v_mfma_f32_16x16x32_bf16 v[62:65], v[146:149], v[196:199], v[62:65]
	v_mfma_f32_16x16x32_bf16 v[58:61], v[172:175], v[196:199], v[58:61]
	v_mfma_f32_16x16x32_bf16 v[46:49], v[146:149], v[204:207], v[46:49]
	v_mfma_f32_16x16x32_bf16 v[42:45], v[172:175], v[204:207], v[42:45]
	v_mfma_f32_16x16x32_bf16 v[30:33], v[146:149], v[220:223], v[30:33]
	v_mfma_f32_16x16x32_bf16 v[26:29], v[172:175], v[220:223], v[26:29]
	v_mfma_f32_16x16x32_bf16 v[14:17], v[146:149], v[228:231], v[14:17]
	v_mfma_f32_16x16x32_bf16 v[10:13], v[172:175], v[228:231], v[10:13]
	v_mfma_f32_16x16x32_bf16 v[54:57], v[176:179], v[192:195], v[54:57]
	v_mfma_f32_16x16x32_bf16 v[50:53], v[184:187], v[192:195], v[50:53]
	v_mfma_f32_16x16x32_bf16 v[38:41], v[176:179], v[200:203], v[38:41]
	v_mfma_f32_16x16x32_bf16 v[34:37], v[184:187], v[200:203], v[34:37]
	v_mfma_f32_16x16x32_bf16 v[22:25], v[176:179], v[216:219], v[22:25]
	v_mfma_f32_16x16x32_bf16 v[18:21], v[184:187], v[216:219], v[18:21]
	v_mfma_f32_16x16x32_bf16 v[6:9], v[176:179], v[224:227], v[6:9]
	v_mfma_f32_16x16x32_bf16 v[2:5], v[184:187], v[224:227], v[2:5]
	v_mfma_f32_16x16x32_bf16 v[54:57], v[180:183], v[196:199], v[54:57]
	v_mfma_f32_16x16x32_bf16 v[50:53], v[188:191], v[196:199], v[50:53]
	v_mfma_f32_16x16x32_bf16 v[38:41], v[180:183], v[204:207], v[38:41]
	v_mfma_f32_16x16x32_bf16 v[34:37], v[188:191], v[204:207], v[34:37]
	v_mfma_f32_16x16x32_bf16 v[22:25], v[180:183], v[220:223], v[22:25]
	v_mfma_f32_16x16x32_bf16 v[18:21], v[188:191], v[220:223], v[18:21]
	v_mfma_f32_16x16x32_bf16 v[6:9], v[180:183], v[228:231], v[6:9]
	v_mfma_f32_16x16x32_bf16 v[2:5], v[188:191], v[228:231], v[2:5]
	s_barrier
	s_add_i32 s29, s29, 2
	s_add_u32 s50, s50, 0x100
	s_addc_u32 s51, s51, 0
	s_add_u32 s17, s17, 0x100
	s_addc_u32 s23, s23, 0
	s_cmp_gt_u32 s29, 29
	s_cbranch_scc0 .LBB0_801
	s_and_b64 vcc, exec, s[20:21]
	s_cbranch_vccz .LBB0_804
	s_barrier

.LBB0_873:
	v_readlane_b32 s0, v240, 63
	s_add_i32 s3, s0, 1
	s_cmp_lt_i32 s3, s93
	s_cselect_b64 s[0:1], -1, 0
	s_and_b64 s[8:9], s[44:45], s[0:1]
	s_andn2_b64 vcc, exec, s[8:9]
	s_mov_b32 s34, 0x10000
	s_cbranch_vccnz .LBB0_923
	s_setprio 0
	s_waitcnt vmcnt(0)
	s_waitcnt vmcnt(0) lgkmcnt(0)
	s_barrier
	s_mov_b64 s[8:9], exec
	v_readlane_b32 s10, v241, 3
	v_readlane_b32 s11, v241, 4
	s_and_b64 s[10:11], s[8:9], s[10:11]
	s_mov_b64 exec, s[10:11]
	s_cbranch_execz .LBB0_922
	v_mov_b32_e32 v1, s97
	s_waitcnt vmcnt(0) expcnt(0) lgkmcnt(0)
	ds_read_b32 v3, v1
	ds_read_b32 v2, v1 offset:4
	s_waitcnt lgkmcnt(1)
	v_cmp_ne_u32_e32 vcc, 0, v3
	s_cbranch_vccnz .LBB0_890
	v_readlane_b32 s12, v244, 0
	v_readlane_b32 s13, v244, 1
	s_load_dwordx2 s[10:11], s[12:13], 0x4
	s_waitcnt lgkmcnt(0)
	s_mul_i32 s10, s10, s96
	s_mul_i32 s10, s10, s11
	s_mov_b32 s11, 1
	s_branch .LBB0_878

.LBB0_1122:
	v_readlane_b32 s0, v240, 63
	s_add_i32 s3, s0, 2
	s_cmp_lt_i32 s3, s93
	s_cselect_b64 s[0:1], -1, 0
	s_and_b64 s[8:9], s[62:63], s[0:1]
	s_andn2_b64 vcc, exec, s[8:9]
	s_cbranch_vccnz .LBB0_1172
	s_setprio 0
	s_waitcnt vmcnt(0)
	s_waitcnt vmcnt(0) lgkmcnt(0)
	s_barrier
	s_mov_b64 s[8:9], exec
	v_readlane_b32 s10, v241, 3
	v_readlane_b32 s11, v241, 4
	s_and_b64 s[10:11], s[8:9], s[10:11]
	s_mov_b64 exec, s[10:11]
	s_cbranch_execz .LBB0_1171
	v_mov_b32_e32 v1, s97
	s_waitcnt vmcnt(0) expcnt(0) lgkmcnt(0)
	ds_read_b32 v3, v1
	ds_read_b32 v2, v1 offset:4
	s_waitcnt lgkmcnt(1)
	v_cmp_ne_u32_e32 vcc, 0, v3
	s_cbranch_vccnz .LBB0_1139
	v_readlane_b32 s12, v244, 0
	v_readlane_b32 s13, v244, 1
	s_load_dwordx2 s[10:11], s[12:13], 0x4
	s_waitcnt lgkmcnt(0)
	s_mul_i32 s10, s10, s96
	s_mul_i32 s10, s10, s11
	s_mov_b32 s11, 1
	s_branch .LBB0_1127

.LBB0_1467:
	v_readlane_b32 s0, v240, 63
	s_add_i32 s3, s0, 3
	s_cmp_lt_i32 s3, s93
	s_cselect_b64 s[0:1], -1, 0
	s_and_b64 s[8:9], s[16:17], s[0:1]
	s_andn2_b64 vcc, exec, s[8:9]
	s_cbranch_vccnz .LBB0_1517
	s_setprio 0
	s_waitcnt vmcnt(0)
	s_waitcnt vmcnt(0) lgkmcnt(0)
	s_barrier
	s_mov_b64 s[8:9], exec
	v_readlane_b32 s10, v241, 3
	v_readlane_b32 s11, v241, 4
	s_and_b64 s[10:11], s[8:9], s[10:11]
	s_mov_b64 exec, s[10:11]
	s_cbranch_execz .LBB0_1516
	v_mov_b32_e32 v1, s97
	s_waitcnt vmcnt(0) expcnt(0) lgkmcnt(0)
	ds_read_b32 v3, v1
	ds_read_b32 v2, v1 offset:4
	s_waitcnt lgkmcnt(1)
	v_cmp_ne_u32_e32 vcc, 0, v3
	s_cbranch_vccnz .LBB0_1484
	v_readlane_b32 s12, v244, 0
	v_readlane_b32 s13, v244, 1
	s_load_dwordx2 s[10:11], s[12:13], 0x4
	s_waitcnt lgkmcnt(0)
	s_mul_i32 s10, s10, s96
	s_mul_i32 s10, s10, s11
	s_mov_b32 s11, 1
	s_branch .LBB0_1472

.LBB0_1545:
	v_readlane_b32 s0, v240, 63
	s_add_i32 s3, s0, 4
	s_cmp_lt_i32 s3, s93
	s_cselect_b64 s[0:1], -1, 0
	s_and_b64 s[8:9], s[8:9], s[0:1]
	s_andn2_b64 vcc, exec, s[8:9]
	s_cbranch_vccnz .LBB0_1595
	s_setprio 0
	s_waitcnt vmcnt(0)
	s_waitcnt vmcnt(0) lgkmcnt(0)
	s_barrier
	s_mov_b64 s[8:9], exec
	v_readlane_b32 s10, v241, 3
	v_readlane_b32 s11, v241, 4
	s_and_b64 s[10:11], s[8:9], s[10:11]
	s_mov_b64 exec, s[10:11]
	s_cbranch_execz .LBB0_1594
	v_mov_b32_e32 v1, s97
	s_waitcnt vmcnt(0) expcnt(0) lgkmcnt(0)
	ds_read_b32 v3, v1
	ds_read_b32 v2, v1 offset:4
	s_waitcnt lgkmcnt(1)
	v_cmp_ne_u32_e32 vcc, 0, v3
	s_cbranch_vccnz .LBB0_1562
	v_readlane_b32 s12, v244, 0
	v_readlane_b32 s13, v244, 1
	s_load_dwordx2 s[10:11], s[12:13], 0x4
	s_waitcnt lgkmcnt(0)
	s_mul_i32 s10, s10, s96
	s_mul_i32 s10, s10, s11
	s_mov_b32 s11, 1
	s_branch .LBB0_1550

.LBB0_1607:
	s_cmp_lg_u64 s[42:43], 0
	s_cbranch_scc0 .Lsp_LBB01607
	s_setprio 1
.Lsp_LBB01607:
	s_add_u32 s14, s64, 0xfff80080
	s_addc_u32 s15, s65, -1
	s_add_i32 s26, 0, 0x10000
	s_cmp_eq_u32 s25, 28
	s_cselect_b32 s67, s23, s15
	s_cselect_b32 s66, s22, s14
	v_add_u32_e32 v147, s26, v144
	s_cselect_b32 s15, s1, s24
	s_cselect_b32 s14, s10, s11
	s_add_i32 s28, 0, 0x14000
	ds_read_b128 v[140:143], v147
	ds_read_b128 v[148:151], v147 offset:1024
	ds_read_b128 v[152:155], v147 offset:2048
	ds_read_b128 v[168:171], v147 offset:3072
	v_add_u32_e32 v147, s28, v144
	ds_read_b128 v[172:175], v147
	ds_read_b128 v[176:179], v147 offset:1024
	ds_read_b128 v[180:183], v147 offset:2048
	ds_read_b128 v[184:187], v147 offset:3072
	v_lshl_add_u64 v[156:157], s[64:65], 0, v[136:137]
	s_add_i32 m0, s13, 0xc000
	ds_read_b128 v[188:191], v146
	ds_read_b128 v[192:195], v146 offset:1024
	ds_read_b128 v[196:199], v146 offset:2048
	ds_read_b128 v[200:203], v146 offset:3072
	ds_read_b128 v[204:207], v146 offset:4096
	ds_read_b128 v[216:219], v146 offset:5120
	ds_read_b128 v[220:223], v146 offset:6144
	ds_read_b128 v[224:227], v146 offset:7168
	global_load_lds_dwordx4 v[156:157], off
	v_lshl_add_u64 v[156:157], s[64:65], 0, v[138:139]
	s_add_i32 m0, s13, 0xe000
	s_nop 0
	global_load_lds_dwordx4 v[156:157], off
	s_waitcnt vmcnt(8)
	s_waitcnt lgkmcnt(0)
	s_barrier
	s_waitcnt lgkmcnt(0)
	v_mfma_f32_16x16x32_bf16 v[126:129], v[140:143], v[188:191], v[126:129]
	v_mfma_f32_16x16x32_bf16 v[122:125], v[152:155], v[188:191], v[122:125]
	v_mfma_f32_16x16x32_bf16 v[110:113], v[140:143], v[196:199], v[110:113]
	v_mfma_f32_16x16x32_bf16 v[106:109], v[152:155], v[196:199], v[106:109]
	v_mfma_f32_16x16x32_bf16 v[94:97], v[140:143], v[204:207], v[94:97]
	v_mfma_f32_16x16x32_bf16 v[90:93], v[152:155], v[204:207], v[90:93]
	v_mfma_f32_16x16x32_bf16 v[78:81], v[140:143], v[220:223], v[78:81]
	v_mfma_f32_16x16x32_bf16 v[74:77], v[152:155], v[220:223], v[74:77]
	v_mfma_f32_16x16x32_bf16 v[126:129], v[148:151], v[192:195], v[126:129]
	v_mfma_f32_16x16x32_bf16 v[122:125], v[168:171], v[192:195], v[122:125]
	v_mfma_f32_16x16x32_bf16 v[110:113], v[148:151], v[200:203], v[110:113]
	v_mfma_f32_16x16x32_bf16 v[106:109], v[168:171], v[200:203], v[106:109]
	v_mfma_f32_16x16x32_bf16 v[94:97], v[148:151], v[216:219], v[94:97]
	v_mfma_f32_16x16x32_bf16 v[90:93], v[168:171], v[216:219], v[90:93]
	v_mfma_f32_16x16x32_bf16 v[78:81], v[148:151], v[224:227], v[78:81]
	v_mfma_f32_16x16x32_bf16 v[74:77], v[168:171], v[224:227], v[74:77]
	v_mfma_f32_16x16x32_bf16 v[118:121], v[172:175], v[188:191], v[118:121]
	v_mfma_f32_16x16x32_bf16 v[114:117], v[180:183], v[188:191], v[114:117]
	v_mfma_f32_16x16x32_bf16 v[102:105], v[172:175], v[196:199], v[102:105]
	v_mfma_f32_16x16x32_bf16 v[98:101], v[180:183], v[196:199], v[98:101]
	v_mfma_f32_16x16x32_bf16 v[86:89], v[172:175], v[204:207], v[86:89]
	v_mfma_f32_16x16x32_bf16 v[82:85], v[180:183], v[204:207], v[82:85]
	v_mfma_f32_16x16x32_bf16 v[70:73], v[172:175], v[220:223], v[70:73]
	v_mfma_f32_16x16x32_bf16 v[66:69], v[180:183], v[220:223], v[66:69]
	v_mfma_f32_16x16x32_bf16 v[118:121], v[176:179], v[192:195], v[118:121]
	v_mfma_f32_16x16x32_bf16 v[114:117], v[184:187], v[192:195], v[114:117]
	v_mfma_f32_16x16x32_bf16 v[102:105], v[176:179], v[200:203], v[102:105]
	v_mfma_f32_16x16x32_bf16 v[98:101], v[184:187], v[200:203], v[98:101]
	v_mfma_f32_16x16x32_bf16 v[86:89], v[176:179], v[216:219], v[86:89]
	v_mfma_f32_16x16x32_bf16 v[82:85], v[184:187], v[216:219], v[82:85]
	v_mfma_f32_16x16x32_bf16 v[70:73], v[176:179], v[224:227], v[70:73]
	v_mfma_f32_16x16x32_bf16 v[66:69], v[184:187], v[224:227], v[66:69]
	s_barrier
	s_add_i32 s26, s26, s17
	v_lshl_add_u64 v[156:157], s[14:15], 0, v[158:159]
	s_mov_b32 m0, s26
	ds_read_b128 v[188:191], v146 offset:16384
	ds_read_b128 v[192:195], v146 offset:17408
	ds_read_b128 v[196:199], v146 offset:18432
	ds_read_b128 v[200:203], v146 offset:19456
	ds_read_b128 v[204:207], v146 offset:20480
	ds_read_b128 v[216:219], v146 offset:21504
	ds_read_b128 v[220:223], v146 offset:22528
	ds_read_b128 v[224:227], v146 offset:23552
	global_load_lds_dwordx4 v[156:157], off
	s_add_i32 m0, s26, 0x2000
	s_add_u32 s26, s14, 0x80000
	v_lshl_add_u64 v[228:229], s[14:15], 0, v[134:135]
	s_addc_u32 s27, s15, 0
	s_add_i32 s28, s28, s17
	global_load_lds_dwordx4 v[228:229], off
	v_lshl_add_u64 v[230:231], s[26:27], 0, v[158:159]
	s_mov_b32 m0, s28
	v_lshl_add_u64 v[232:233], s[66:67], 0, v[132:133]
	global_load_lds_dwordx4 v[230:231], off
	v_lshl_add_u64 v[230:231], s[26:27], 0, v[134:135]
	s_add_i32 m0, s28, 0x2000
	s_nop 0
	global_load_lds_dwordx4 v[230:231], off
	v_lshl_add_u64 v[230:231], s[66:67], 0, v[130:131]
	s_mov_b32 m0, s13
	s_nop 0
	global_load_lds_dwordx4 v[230:231], off
	s_mov_b32 m0, s53
	s_nop 0
	global_load_lds_dwordx4 v[232:233], off
	s_waitcnt vmcnt(8)
	s_waitcnt lgkmcnt(0)
	s_barrier
	s_waitcnt lgkmcnt(0)
	v_mfma_f32_16x16x32_bf16 v[62:65], v[140:143], v[188:191], v[62:65]
	v_mfma_f32_16x16x32_bf16 v[58:61], v[152:155], v[188:191], v[58:61]
	v_mfma_f32_16x16x32_bf16 v[46:49], v[140:143], v[196:199], v[46:49]
	v_mfma_f32_16x16x32_bf16 v[42:45], v[152:155], v[196:199], v[42:45]
	v_mfma_f32_16x16x32_bf16 v[30:33], v[140:143], v[204:207], v[30:33]
	v_mfma_f32_16x16x32_bf16 v[26:29], v[152:155], v[204:207], v[26:29]
	v_mfma_f32_16x16x32_bf16 v[14:17], v[140:143], v[220:223], v[14:17]
	v_mfma_f32_16x16x32_bf16 v[10:13], v[152:155], v[220:223], v[10:13]
	v_mfma_f32_16x16x32_bf16 v[62:65], v[148:151], v[192:195], v[62:65]
	v_mfma_f32_16x16x32_bf16 v[58:61], v[168:171], v[192:195], v[58:61]
	v_mfma_f32_16x16x32_bf16 v[46:49], v[148:151], v[200:203], v[46:49]
	v_mfma_f32_16x16x32_bf16 v[42:45], v[168:171], v[200:203], v[42:45]
	v_mfma_f32_16x16x32_bf16 v[30:33], v[148:151], v[216:219], v[30:33]
	v_mfma_f32_16x16x32_bf16 v[26:29], v[168:171], v[216:219], v[26:29]
	v_mfma_f32_16x16x32_bf16 v[14:17], v[148:151], v[224:227], v[14:17]
	v_mfma_f32_16x16x32_bf16 v[10:13], v[168:171], v[224:227], v[10:13]
	v_mfma_f32_16x16x32_bf16 v[54:57], v[172:175], v[188:191], v[54:57]
	v_mfma_f32_16x16x32_bf16 v[50:53], v[180:183], v[188:191], v[50:53]
	v_mfma_f32_16x16x32_bf16 v[38:41], v[172:175], v[196:199], v[38:41]
	v_mfma_f32_16x16x32_bf16 v[34:37], v[180:183], v[196:199], v[34:37]
	v_mfma_f32_16x16x32_bf16 v[22:25], v[172:175], v[204:207], v[22:25]
	v_mfma_f32_16x16x32_bf16 v[18:21], v[180:183], v[204:207], v[18:21]
	v_mfma_f32_16x16x32_bf16 v[6:9], v[172:175], v[220:223], v[6:9]
	v_mfma_f32_16x16x32_bf16 v[2:5], v[180:183], v[220:223], v[2:5]
	v_mfma_f32_16x16x32_bf16 v[54:57], v[176:179], v[192:195], v[54:57]
	v_mfma_f32_16x16x32_bf16 v[50:53], v[184:187], v[192:195], v[50:53]
	v_mfma_f32_16x16x32_bf16 v[38:41], v[176:179], v[200:203], v[38:41]
	v_mfma_f32_16x16x32_bf16 v[34:37], v[184:187], v[200:203], v[34:37]
	v_mfma_f32_16x16x32_bf16 v[22:25], v[176:179], v[216:219], v[22:25]
	v_mfma_f32_16x16x32_bf16 v[18:21], v[184:187], v[216:219], v[18:21]
	v_mfma_f32_16x16x32_bf16 v[6:9], v[176:179], v[224:227], v[6:9]
	v_mfma_f32_16x16x32_bf16 v[2:5], v[184:187], v[224:227], v[2:5]
	s_barrier
	s_add_i32 s28, 0, 0x18000
	v_add_u32_e32 v147, s28, v144
	s_add_i32 s29, 0, 0x1c000
	ds_read_b128 v[140:143], v147
	ds_read_b128 v[148:151], v147 offset:1024
	ds_read_b128 v[152:155], v147 offset:2048
	ds_read_b128 v[168:171], v147 offset:3072
	v_add_u32_e32 v147, s29, v144
	ds_read_b128 v[172:175], v147
	ds_read_b128 v[176:179], v147 offset:1024
	ds_read_b128 v[180:183], v147 offset:2048
	ds_read_b128 v[184:187], v147 offset:3072
	s_add_u32 s26, s66, 0x80000
	s_addc_u32 s27, s67, 0
	s_mov_b32 m0, s58
	v_lshl_add_u64 v[234:235], s[26:27], 0, v[130:131]
	ds_read_b128 v[188:191], v146 offset:32768
	ds_read_b128 v[192:195], v146 offset:33792
	ds_read_b128 v[196:199], v146 offset:34816
	ds_read_b128 v[200:203], v146 offset:35840
	ds_read_b128 v[204:207], v146 offset:36864
	ds_read_b128 v[216:219], v146 offset:37888
	ds_read_b128 v[220:223], v146 offset:38912
	ds_read_b128 v[224:227], v146 offset:39936
	global_load_lds_dwordx4 v[234:235], off
	v_lshl_add_u64 v[234:235], s[26:27], 0, v[132:133]
	s_mov_b32 m0, s59
	s_nop 0
	global_load_lds_dwordx4 v[234:235], off
	s_waitcnt vmcnt(8)
	s_waitcnt lgkmcnt(0)
	s_barrier
	s_waitcnt lgkmcnt(0)
	v_mfma_f32_16x16x32_bf16 v[126:129], v[140:143], v[188:191], v[126:129]
	v_mfma_f32_16x16x32_bf16 v[122:125], v[152:155], v[188:191], v[122:125]
	v_mfma_f32_16x16x32_bf16 v[110:113], v[140:143], v[196:199], v[110:113]
	v_mfma_f32_16x16x32_bf16 v[106:109], v[152:155], v[196:199], v[106:109]
	v_mfma_f32_16x16x32_bf16 v[94:97], v[140:143], v[204:207], v[94:97]
	v_mfma_f32_16x16x32_bf16 v[90:93], v[152:155], v[204:207], v[90:93]
	v_mfma_f32_16x16x32_bf16 v[78:81], v[140:143], v[220:223], v[78:81]
	v_mfma_f32_16x16x32_bf16 v[74:77], v[152:155], v[220:223], v[74:77]
	v_mfma_f32_16x16x32_bf16 v[126:129], v[148:151], v[192:195], v[126:129]
	v_mfma_f32_16x16x32_bf16 v[122:125], v[168:171], v[192:195], v[122:125]
	v_mfma_f32_16x16x32_bf16 v[110:113], v[148:151], v[200:203], v[110:113]
	v_mfma_f32_16x16x32_bf16 v[106:109], v[168:171], v[200:203], v[106:109]
	v_mfma_f32_16x16x32_bf16 v[94:97], v[148:151], v[216:219], v[94:97]
	v_mfma_f32_16x16x32_bf16 v[90:93], v[168:171], v[216:219], v[90:93]
	v_mfma_f32_16x16x32_bf16 v[78:81], v[148:151], v[224:227], v[78:81]
	v_mfma_f32_16x16x32_bf16 v[74:77], v[168:171], v[224:227], v[74:77]
	v_mfma_f32_16x16x32_bf16 v[118:121], v[172:175], v[188:191], v[118:121]
	v_mfma_f32_16x16x32_bf16 v[114:117], v[180:183], v[188:191], v[114:117]
	v_mfma_f32_16x16x32_bf16 v[102:105], v[172:175], v[196:199], v[102:105]
	v_mfma_f32_16x16x32_bf16 v[98:101], v[180:183], v[196:199], v[98:101]
	v_mfma_f32_16x16x32_bf16 v[86:89], v[172:175], v[204:207], v[86:89]
	v_mfma_f32_16x16x32_bf16 v[82:85], v[180:183], v[204:207], v[82:85]
	v_mfma_f32_16x16x32_bf16 v[70:73], v[172:175], v[220:223], v[70:73]
	v_mfma_f32_16x16x32_bf16 v[66:69], v[180:183], v[220:223], v[66:69]
	v_mfma_f32_16x16x32_bf16 v[118:121], v[176:179], v[192:195], v[118:121]
	v_mfma_f32_16x16x32_bf16 v[114:117], v[184:187], v[192:195], v[114:117]
	v_mfma_f32_16x16x32_bf16 v[102:105], v[176:179], v[200:203], v[102:105]
	v_mfma_f32_16x16x32_bf16 v[98:101], v[184:187], v[200:203], v[98:101]
	v_mfma_f32_16x16x32_bf16 v[86:89], v[176:179], v[216:219], v[86:89]
	v_mfma_f32_16x16x32_bf16 v[82:85], v[184:187], v[216:219], v[82:85]
	v_mfma_f32_16x16x32_bf16 v[70:73], v[176:179], v[224:227], v[70:73]
	v_mfma_f32_16x16x32_bf16 v[66:69], v[184:187], v[224:227], v[66:69]
	s_barrier
	s_add_i32 s26, s28, s17
	v_lshl_add_u64 v[156:157], v[156:157], 0, s[56:57]
	s_mov_b32 m0, s26
	ds_read_b128 v[188:191], v146 offset:49152
	ds_read_b128 v[192:195], v146 offset:50176
	ds_read_b128 v[196:199], v146 offset:51200
	ds_read_b128 v[200:203], v146 offset:52224
	ds_read_b128 v[204:207], v146 offset:53248
	ds_read_b128 v[216:219], v146 offset:54272
	ds_read_b128 v[220:223], v146 offset:55296
	ds_read_b128 v[224:227], v146 offset:56320
	global_load_lds_dwordx4 v[156:157], off
	s_add_i32 m0, s26, 0x2000
	s_add_u32 s14, s14, 0x80080
	v_lshl_add_u64 v[156:157], v[228:229], 0, s[56:57]
	s_addc_u32 s15, s15, 0
	s_add_i32 s26, s29, s17
	global_load_lds_dwordx4 v[156:157], off
	v_lshl_add_u64 v[156:157], s[14:15], 0, v[158:159]
	s_mov_b32 m0, s26
	s_nop 0
	global_load_lds_dwordx4 v[156:157], off
	v_lshl_add_u64 v[156:157], s[14:15], 0, v[134:135]
	s_add_i32 m0, s26, 0x2000
	s_nop 0
	global_load_lds_dwordx4 v[156:157], off
	v_lshl_add_u64 v[156:157], v[230:231], 0, s[56:57]
	s_mov_b32 m0, s54
	s_nop 0
	global_load_lds_dwordx4 v[156:157], off
	v_lshl_add_u64 v[156:157], v[232:233], 0, s[56:57]
	s_mov_b32 m0, s68
	s_nop 0
	global_load_lds_dwordx4 v[156:157], off
	s_waitcnt vmcnt(8)
	s_waitcnt lgkmcnt(0)
	s_barrier
	s_waitcnt lgkmcnt(0)
	v_mfma_f32_16x16x32_bf16 v[62:65], v[140:143], v[188:191], v[62:65]
	v_mfma_f32_16x16x32_bf16 v[58:61], v[152:155], v[188:191], v[58:61]
	v_mfma_f32_16x16x32_bf16 v[46:49], v[140:143], v[196:199], v[46:49]
	v_mfma_f32_16x16x32_bf16 v[42:45], v[152:155], v[196:199], v[42:45]
	v_mfma_f32_16x16x32_bf16 v[30:33], v[140:143], v[204:207], v[30:33]
	v_mfma_f32_16x16x32_bf16 v[26:29], v[152:155], v[204:207], v[26:29]
	v_mfma_f32_16x16x32_bf16 v[14:17], v[140:143], v[220:223], v[14:17]
	v_mfma_f32_16x16x32_bf16 v[10:13], v[152:155], v[220:223], v[10:13]
	v_mfma_f32_16x16x32_bf16 v[62:65], v[148:151], v[192:195], v[62:65]
	v_mfma_f32_16x16x32_bf16 v[58:61], v[168:171], v[192:195], v[58:61]
	v_mfma_f32_16x16x32_bf16 v[46:49], v[148:151], v[200:203], v[46:49]
	v_mfma_f32_16x16x32_bf16 v[42:45], v[168:171], v[200:203], v[42:45]
	v_mfma_f32_16x16x32_bf16 v[30:33], v[148:151], v[216:219], v[30:33]
	v_mfma_f32_16x16x32_bf16 v[26:29], v[168:171], v[216:219], v[26:29]
	v_mfma_f32_16x16x32_bf16 v[14:17], v[148:151], v[224:227], v[14:17]
	v_mfma_f32_16x16x32_bf16 v[10:13], v[168:171], v[224:227], v[10:13]
	v_mfma_f32_16x16x32_bf16 v[54:57], v[172:175], v[188:191], v[54:57]
	v_mfma_f32_16x16x32_bf16 v[50:53], v[180:183], v[188:191], v[50:53]
	v_mfma_f32_16x16x32_bf16 v[38:41], v[172:175], v[196:199], v[38:41]
	v_mfma_f32_16x16x32_bf16 v[34:37], v[180:183], v[196:199], v[34:37]
	v_mfma_f32_16x16x32_bf16 v[22:25], v[172:175], v[204:207], v[22:25]
	v_mfma_f32_16x16x32_bf16 v[18:21], v[180:183], v[204:207], v[18:21]
	v_mfma_f32_16x16x32_bf16 v[6:9], v[172:175], v[220:223], v[6:9]
	v_mfma_f32_16x16x32_bf16 v[2:5], v[180:183], v[220:223], v[2:5]
	v_mfma_f32_16x16x32_bf16 v[54:57], v[176:179], v[192:195], v[54:57]
	v_mfma_f32_16x16x32_bf16 v[50:53], v[184:187], v[192:195], v[50:53]
	v_mfma_f32_16x16x32_bf16 v[38:41], v[176:179], v[200:203], v[38:41]
	v_mfma_f32_16x16x32_bf16 v[34:37], v[184:187], v[200:203], v[34:37]
	v_mfma_f32_16x16x32_bf16 v[22:25], v[176:179], v[216:219], v[22:25]
	v_mfma_f32_16x16x32_bf16 v[18:21], v[184:187], v[216:219], v[18:21]
	v_mfma_f32_16x16x32_bf16 v[6:9], v[176:179], v[224:227], v[6:9]
	v_mfma_f32_16x16x32_bf16 v[2:5], v[184:187], v[224:227], v[2:5]
	s_barrier
	s_add_i32 s25, s25, 2
	s_add_u32 s64, s64, 0x100
	s_addc_u32 s65, s65, 0
	s_add_u32 s11, s11, 0x100
	s_addc_u32 s24, s24, 0
	s_cmp_gt_u32 s25, 29
	s_cbranch_scc0 .LBB0_1607
	s_and_b64 vcc, exec, s[42:43]
	s_cbranch_vccz .LBB0_1610
	s_barrier

.LBB0_1630:
	v_readlane_b32 s0, v240, 63
	s_add_i32 s3, s0, 5
	s_cmp_lt_i32 s3, s93
	s_cselect_b64 s[0:1], -1, 0
	s_and_b64 s[0:1], s[18:19], s[0:1]
	v_readlane_b32 s34, v241, 13
	s_andn2_b64 vcc, exec, s[0:1]
	v_readlane_b32 s35, v241, 14
	s_cbranch_vccnz .LBB0_1680
	s_setprio 0
	s_waitcnt vmcnt(0)
	s_waitcnt vmcnt(0) lgkmcnt(0)
	s_barrier
	s_mov_b64 s[0:1], exec
	v_readlane_b32 s8, v241, 3
	v_readlane_b32 s9, v241, 4
	s_and_b64 s[8:9], s[0:1], s[8:9]
	s_mov_b64 exec, s[8:9]
	s_cbranch_execz .LBB0_1679
	v_mov_b32_e32 v1, s97
	s_waitcnt vmcnt(0) expcnt(0) lgkmcnt(0)
	ds_read_b32 v3, v1
	ds_read_b32 v2, v1 offset:4
	s_waitcnt lgkmcnt(1)
	v_cmp_ne_u32_e32 vcc, 0, v3
	s_cbranch_vccnz .LBB0_1647
	v_readlane_b32 s10, v244, 0
	v_readlane_b32 s11, v244, 1
	s_load_dwordx2 s[8:9], s[10:11], 0x4
	s_mov_b32 s11, 1
	s_waitcnt lgkmcnt(0)
	s_mul_i32 s10, s8, s96
	s_mul_i32 s10, s10, s9
	s_branch .LBB0_1635
